# static priority: one s_setprio 1 for waves 4-7 at each GEMM phase entry, the per-MMA-block priority flips deleted
# baseline (speedup 1.0000x reference)
.LBB0_116:
	s_cmp_lt_i32 s76, 3
	s_cselect_b64 s[20:21], -1, 0
	s_and_b64 s[4:5], s[20:21], s[46:47]
	s_andn2_b64 vcc, exec, s[4:5]
	s_cbranch_vccnz .LBB0_296
	s_cmpk_gt_i32 s2, 0x1a27
	s_mov_b64 s[6:7], s[0:1]
	v_readfirstlane_b32 s22, v196
	s_waitcnt lgkmcnt(0)
	s_barrier
	s_cbranch_scc1 .LBB0_296
	s_lshr_b32 s99, s22, 8
	s_cmp_eq_u32 s99, 1
	s_cbranch_scc0 .Lprio_p2
	s_setprio 1
.Lprio_p2:
	v_lshrrev_b32_e32 v2, 1, v196
	v_lshrrev_b32_e32 v3, 5, v196
	v_and_b32_e32 v2, 24, v2
	v_and_b32_e32 v3, 4, v3
	v_bfe_u32 v4, v196, 2, 2
	v_lshlrev_b32_e32 v0, 4, v196
	v_and_b32_e32 v1, 32, v196
	v_bfe_u32 v10, v196, 2, 4
	v_or3_b32 v2, v3, v4, v2
	v_lshrrev_b32_e32 v3, 3, v196
	s_movk_i32 s3, 0x70
	v_bitop3_b32 v8, v0, v1, 48 bitop3:0x6c
	v_and_b32_e32 v9, 64, v196
	v_and_or_b32 v4, v3, s3, v10
	s_movk_i32 s3, 0x60
	v_add_u32_e32 v11, 0x2000, v0
	v_or_b32_e32 v1, v8, v9
	v_and_or_b32 v3, v3, s3, v2
	v_lshrrev_b32_e32 v0, 7, v11
	s_movk_i32 s3, 0xf0
	v_lshl_or_b32 v130, v3, 11, v1
	v_and_or_b32 v3, v0, s3, v10
	s_movk_i32 s3, 0xe0
	v_and_or_b32 v0, v0, s3, v2
	s_and_b32 s3, s2, 0xff
	s_mulk_i32 s3, 0xcd
	s_lshr_b32 s3, s3, 10
	s_or_b32 s8, s3, 0x100
	s_mul_i32 s3, s3, 5
	s_sub_i32 s3, s2, s3
	s_and_b32 s9, s3, 0xff
	s_ashr_i32 s3, s2, 31
	s_lshr_b32 s4, s3, 29
	s_add_i32 s4, s2, s4
	s_and_b32 s5, s4, -8
	s_sub_i32 s5, s2, s5
	s_cmp_lt_i32 s5, 0
	s_movk_i32 s39, 0x341
	s_cselect_b32 s10, s39, 0x340
	s_mul_i32 s5, s10, s5
	s_ashr_i32 s4, s4, 3
	s_add_i32 s5, s5, s4
	s_mul_hi_i32 s4, s5, 0x4ec4ec4f
	s_lshr_b32 s10, s4, 31
	s_ashr_i32 s4, s4, 6
	s_add_i32 s4, s4, s10
	s_lshl_b32 s10, s4, 3
	s_mulk_i32 s4, 0xd0
	s_sub_i32 s4, s5, s4
	s_sext_i32_i16 s5, s4
	s_bfe_u32 s5, s5, 0x3001c
	s_add_i32 s5, s4, s5
	s_sext_i32_i16 s11, s5
	s_and_b32 s5, s5, 0xfff8
	s_sub_i32 s4, s4, s5
	s_sext_i32_i16 s4, s4
	s_lshr_b32 s5, s22, 6
	s_add_i32 s10, s10, s4
	s_ashr_i32 s11, s11, 3
	s_lshr_b32 s4, s22, 8
	s_lshl_b32 s47, s5, 10
	s_load_dwordx4 s[16:19], s[6:7], 0xd8
	s_cmpk_lt_i32 s2, 0x1a00
	s_cselect_b32 s12, s10, s8
	s_cselect_b32 s10, s11, s9
	s_ashr_i32 s13, s12, 31
	s_ashr_i32 s11, s10, 31
	s_lshl_b64 s[6:7], s[12:13], 19
	s_lshl_b64 s[8:9], s[10:11], 19
	s_waitcnt lgkmcnt(0)
	s_add_u32 s8, s18, s8
	s_addc_u32 s9, s19, s9
	s_add_i32 s60, s47, 0
	s_add_i32 m0, s60, 0x10000
	v_lshl_or_b32 v134, v0, 11, v1
	global_load_lds_dwordx4 v130, s[8:9]
	s_add_i32 m0, s60, 0x12000
	s_add_u32 s14, s8, 0x40000
	global_load_lds_dwordx4 v134, s[8:9]
	s_addc_u32 s15, s9, 0
	s_add_i32 m0, s60, 0x14000
	v_lshl_or_b32 v128, v4, 11, v1
	global_load_lds_dwordx4 v130, s[14:15]
	s_add_i32 m0, s60, 0x16000
	v_lshl_or_b32 v132, v3, 11, v1
	global_load_lds_dwordx4 v134, s[14:15]
	s_add_u32 s14, s16, s6
	s_addc_u32 s15, s17, s7
	s_add_i32 s61, s60, 0x2000
	s_mov_b32 m0, s60
	s_add_u32 s6, s14, 0x40000
	global_load_lds_dwordx4 v128, s[14:15]
	s_mov_b32 m0, s61
	s_addc_u32 s7, s15, 0
	s_add_i32 s62, s60, 0x4000
	global_load_lds_dwordx4 v132, s[14:15]
	s_mov_b32 m0, s62
	s_add_i32 s63, s60, 0x6000
	global_load_lds_dwordx4 v128, s[6:7]
	s_mov_b32 m0, s63
	v_mov_b32_e32 v131, 0
	global_load_lds_dwordx4 v132, s[6:7]
	v_mov_b32_e32 v135, v131
	v_mov_b32_e32 v129, v131
	v_mov_b32_e32 v133, v131
	s_cmp_eq_u32 s4, 1
	s_mov_b32 s23, 0
	v_lshl_add_u64 v[6:7], s[8:9], 0, v[130:131]
	v_lshl_add_u64 v[4:5], s[8:9], 0, v[134:135]
	v_lshl_add_u64 v[0:1], s[14:15], 0, v[128:129]
	s_cselect_b64 s[24:25], -1, 0
	s_cmp_lg_u32 s4, 1
	v_lshl_add_u64 v[2:3], s[14:15], 0, v[132:133]
	s_cbranch_scc1 .LBB0_120
	s_barrier

.LBB0_129:
	ds_read_b128 v[148:151], v156
	ds_read_b128 v[160:163], v156 offset:1024
	ds_read_b128 v[164:167], v156 offset:2048
	ds_read_b128 v[168:171], v156 offset:3072
	ds_read_b128 v[172:175], v157
	ds_read_b128 v[176:179], v157 offset:1024
	ds_read_b128 v[180:183], v157 offset:2048
	ds_read_b128 v[184:187], v157 offset:3072
	s_add_u32 s4, s8, 0xfffc0080
	s_addc_u32 s5, s9, -1
	s_cmp_eq_u32 s59, 12
	s_cselect_b32 s57, s11, s5
	s_cselect_b32 s56, s13, s4
	s_cselect_b32 s15, s22, s58
	s_cselect_b32 s14, s49, s51
	v_lshl_add_u64 v[152:153], s[8:9], 0, v[138:139]
	s_add_i32 m0, s60, 0xc000
	ds_read_b128 v[188:191], v158
	ds_read_b128 v[192:195], v158 offset:1024
	ds_read_b128 v[198:201], v158 offset:2048
	ds_read_b128 v[202:205], v158 offset:3072
	ds_read_b128 v[206:209], v158 offset:4096
	ds_read_b128 v[210:213], v158 offset:5120
	ds_read_b128 v[214:217], v158 offset:6144
	ds_read_b128 v[218:221], v158 offset:7168
	global_load_lds_dwordx4 v[152:153], off
	v_lshl_add_u64 v[152:153], s[8:9], 0, v[136:137]
	s_add_i32 m0, s60, 0xe000
	s_nop 0
	global_load_lds_dwordx4 v[152:153], off
	s_waitcnt vmcnt(8)
	s_waitcnt lgkmcnt(0)
	s_barrier
	s_waitcnt lgkmcnt(0)
	v_mfma_f32_16x16x32_bf16 v[124:127], v[148:151], v[188:191], v[124:127]
	v_mfma_f32_16x16x32_bf16 v[120:123], v[164:167], v[188:191], v[120:123]
	v_mfma_f32_16x16x32_bf16 v[108:111], v[148:151], v[198:201], v[108:111]
	v_mfma_f32_16x16x32_bf16 v[104:107], v[164:167], v[198:201], v[104:107]
	v_mfma_f32_16x16x32_bf16 v[92:95], v[148:151], v[206:209], v[92:95]
	v_mfma_f32_16x16x32_bf16 v[88:91], v[164:167], v[206:209], v[88:91]
	v_mfma_f32_16x16x32_bf16 v[76:79], v[148:151], v[214:217], v[76:79]
	v_mfma_f32_16x16x32_bf16 v[72:75], v[164:167], v[214:217], v[72:75]
	v_mfma_f32_16x16x32_bf16 v[124:127], v[160:163], v[192:195], v[124:127]
	v_mfma_f32_16x16x32_bf16 v[120:123], v[168:171], v[192:195], v[120:123]
	v_mfma_f32_16x16x32_bf16 v[108:111], v[160:163], v[202:205], v[108:111]
	v_mfma_f32_16x16x32_bf16 v[104:107], v[168:171], v[202:205], v[104:107]
	v_mfma_f32_16x16x32_bf16 v[92:95], v[160:163], v[210:213], v[92:95]
	v_mfma_f32_16x16x32_bf16 v[88:91], v[168:171], v[210:213], v[88:91]
	v_mfma_f32_16x16x32_bf16 v[76:79], v[160:163], v[218:221], v[76:79]
	v_mfma_f32_16x16x32_bf16 v[72:75], v[168:171], v[218:221], v[72:75]
	v_mfma_f32_16x16x32_bf16 v[116:119], v[172:175], v[188:191], v[116:119]
	v_mfma_f32_16x16x32_bf16 v[112:115], v[180:183], v[188:191], v[112:115]
	v_mfma_f32_16x16x32_bf16 v[100:103], v[172:175], v[198:201], v[100:103]
	v_mfma_f32_16x16x32_bf16 v[96:99], v[180:183], v[198:201], v[96:99]
	v_mfma_f32_16x16x32_bf16 v[84:87], v[172:175], v[206:209], v[84:87]
	v_mfma_f32_16x16x32_bf16 v[80:83], v[180:183], v[206:209], v[80:83]
	v_mfma_f32_16x16x32_bf16 v[68:71], v[172:175], v[214:217], v[68:71]
	v_mfma_f32_16x16x32_bf16 v[64:67], v[180:183], v[214:217], v[64:67]
	v_mfma_f32_16x16x32_bf16 v[116:119], v[176:179], v[192:195], v[116:119]
	v_mfma_f32_16x16x32_bf16 v[112:115], v[184:187], v[192:195], v[112:115]
	v_mfma_f32_16x16x32_bf16 v[100:103], v[176:179], v[202:205], v[100:103]
	v_mfma_f32_16x16x32_bf16 v[96:99], v[184:187], v[202:205], v[96:99]
	v_mfma_f32_16x16x32_bf16 v[84:87], v[176:179], v[210:213], v[84:87]
	v_mfma_f32_16x16x32_bf16 v[80:83], v[184:187], v[210:213], v[80:83]
	v_mfma_f32_16x16x32_bf16 v[68:71], v[176:179], v[218:221], v[68:71]
	v_mfma_f32_16x16x32_bf16 v[64:67], v[184:187], v[218:221], v[64:67]
	s_barrier
	s_add_i32 s4, s70, s47
	v_lshl_add_u64 v[152:153], s[14:15], 0, v[130:131]
	s_mov_b32 m0, s4
	ds_read_b128 v[188:191], v158 offset:16384
	ds_read_b128 v[192:195], v158 offset:17408
	ds_read_b128 v[198:201], v158 offset:18432
	ds_read_b128 v[202:205], v158 offset:19456
	ds_read_b128 v[206:209], v158 offset:20480
	ds_read_b128 v[210:213], v158 offset:21504
	ds_read_b128 v[214:217], v158 offset:22528
	ds_read_b128 v[218:221], v158 offset:23552
	global_load_lds_dwordx4 v[152:153], off
	s_add_i32 m0, s4, 0x2000
	s_add_u32 s4, s14, 0x40000
	v_lshl_add_u64 v[222:223], s[14:15], 0, v[134:135]
	s_addc_u32 s5, s15, 0
	s_add_i32 s33, s71, s47
	global_load_lds_dwordx4 v[222:223], off
	v_lshl_add_u64 v[224:225], s[4:5], 0, v[130:131]
	s_mov_b32 m0, s33
	v_lshl_add_u64 v[226:227], s[56:57], 0, v[132:133]
	global_load_lds_dwordx4 v[224:225], off
	v_lshl_add_u64 v[224:225], s[4:5], 0, v[134:135]
	s_add_i32 m0, s33, 0x2000
	s_nop 0
	global_load_lds_dwordx4 v[224:225], off
	v_lshl_add_u64 v[224:225], s[56:57], 0, v[128:129]
	s_mov_b32 m0, s60
	s_nop 0
	global_load_lds_dwordx4 v[224:225], off
	s_mov_b32 m0, s61
	s_nop 0
	global_load_lds_dwordx4 v[226:227], off
	s_waitcnt vmcnt(8)
	s_waitcnt lgkmcnt(0)
	s_barrier
	s_waitcnt lgkmcnt(0)
	v_mfma_f32_16x16x32_bf16 v[60:63], v[148:151], v[188:191], v[60:63]
	v_mfma_f32_16x16x32_bf16 v[56:59], v[164:167], v[188:191], v[56:59]
	v_mfma_f32_16x16x32_bf16 v[44:47], v[148:151], v[198:201], v[44:47]
	v_mfma_f32_16x16x32_bf16 v[40:43], v[164:167], v[198:201], v[40:43]
	v_mfma_f32_16x16x32_bf16 v[28:31], v[148:151], v[206:209], v[28:31]
	v_mfma_f32_16x16x32_bf16 v[24:27], v[164:167], v[206:209], v[24:27]
	v_mfma_f32_16x16x32_bf16 v[12:15], v[148:151], v[214:217], v[12:15]
	v_mfma_f32_16x16x32_bf16 v[8:11], v[164:167], v[214:217], v[8:11]
	v_mfma_f32_16x16x32_bf16 v[60:63], v[160:163], v[192:195], v[60:63]
	v_mfma_f32_16x16x32_bf16 v[56:59], v[168:171], v[192:195], v[56:59]
	v_mfma_f32_16x16x32_bf16 v[44:47], v[160:163], v[202:205], v[44:47]
	v_mfma_f32_16x16x32_bf16 v[40:43], v[168:171], v[202:205], v[40:43]
	v_mfma_f32_16x16x32_bf16 v[28:31], v[160:163], v[210:213], v[28:31]
	v_mfma_f32_16x16x32_bf16 v[24:27], v[168:171], v[210:213], v[24:27]
	v_mfma_f32_16x16x32_bf16 v[12:15], v[160:163], v[218:221], v[12:15]
	v_mfma_f32_16x16x32_bf16 v[8:11], v[168:171], v[218:221], v[8:11]
	v_mfma_f32_16x16x32_bf16 v[52:55], v[172:175], v[188:191], v[52:55]
	v_mfma_f32_16x16x32_bf16 v[48:51], v[180:183], v[188:191], v[48:51]
	v_mfma_f32_16x16x32_bf16 v[36:39], v[172:175], v[198:201], v[36:39]
	v_mfma_f32_16x16x32_bf16 v[32:35], v[180:183], v[198:201], v[32:35]
	v_mfma_f32_16x16x32_bf16 v[20:23], v[172:175], v[206:209], v[20:23]
	v_mfma_f32_16x16x32_bf16 v[16:19], v[180:183], v[206:209], v[16:19]
	v_mfma_f32_16x16x32_bf16 v[4:7], v[172:175], v[214:217], v[4:7]
	v_mfma_f32_16x16x32_bf16 v[0:3], v[180:183], v[214:217], v[0:3]
	v_mfma_f32_16x16x32_bf16 v[52:55], v[176:179], v[192:195], v[52:55]
	v_mfma_f32_16x16x32_bf16 v[48:51], v[184:187], v[192:195], v[48:51]
	v_mfma_f32_16x16x32_bf16 v[36:39], v[176:179], v[202:205], v[36:39]
	v_mfma_f32_16x16x32_bf16 v[32:35], v[184:187], v[202:205], v[32:35]
	v_mfma_f32_16x16x32_bf16 v[20:23], v[176:179], v[210:213], v[20:23]
	v_mfma_f32_16x16x32_bf16 v[16:19], v[184:187], v[210:213], v[16:19]
	v_mfma_f32_16x16x32_bf16 v[4:7], v[176:179], v[218:221], v[4:7]
	v_mfma_f32_16x16x32_bf16 v[0:3], v[184:187], v[218:221], v[0:3]
	s_barrier
	s_add_i32 s33, 0, 0x18000
	s_add_i32 s40, 0, 0x1c000
	v_add_u32_e32 v168, s33, v155
	v_add_u32_e32 v184, s40, v155
	ds_read_b128 v[148:151], v168
	ds_read_b128 v[160:163], v168 offset:1024
	ds_read_b128 v[164:167], v168 offset:2048
	ds_read_b128 v[168:171], v168 offset:3072
	ds_read_b128 v[172:175], v184
	ds_read_b128 v[176:179], v184 offset:1024
	ds_read_b128 v[180:183], v184 offset:2048
	ds_read_b128 v[184:187], v184 offset:3072
	s_add_u32 s4, s56, 0x40000
	s_addc_u32 s5, s57, 0
	s_mov_b32 m0, s62
	v_lshl_add_u64 v[228:229], s[4:5], 0, v[128:129]
	ds_read_b128 v[188:191], v158 offset:32768
	ds_read_b128 v[192:195], v158 offset:33792
	ds_read_b128 v[198:201], v158 offset:34816
	ds_read_b128 v[202:205], v158 offset:35840
	ds_read_b128 v[206:209], v158 offset:36864
	ds_read_b128 v[210:213], v158 offset:37888
	ds_read_b128 v[214:217], v158 offset:38912
	ds_read_b128 v[218:221], v158 offset:39936
	global_load_lds_dwordx4 v[228:229], off
	v_lshl_add_u64 v[228:229], s[4:5], 0, v[132:133]
	s_mov_b32 m0, s63
	s_nop 0
	global_load_lds_dwordx4 v[228:229], off
	s_waitcnt vmcnt(8)
	s_waitcnt lgkmcnt(0)
	s_barrier
	s_waitcnt lgkmcnt(0)
	v_mfma_f32_16x16x32_bf16 v[124:127], v[148:151], v[188:191], v[124:127]
	v_mfma_f32_16x16x32_bf16 v[120:123], v[164:167], v[188:191], v[120:123]
	v_mfma_f32_16x16x32_bf16 v[108:111], v[148:151], v[198:201], v[108:111]
	v_mfma_f32_16x16x32_bf16 v[104:107], v[164:167], v[198:201], v[104:107]
	v_mfma_f32_16x16x32_bf16 v[92:95], v[148:151], v[206:209], v[92:95]
	v_mfma_f32_16x16x32_bf16 v[88:91], v[164:167], v[206:209], v[88:91]
	v_mfma_f32_16x16x32_bf16 v[76:79], v[148:151], v[214:217], v[76:79]
	v_mfma_f32_16x16x32_bf16 v[72:75], v[164:167], v[214:217], v[72:75]
	v_mfma_f32_16x16x32_bf16 v[124:127], v[160:163], v[192:195], v[124:127]
	v_mfma_f32_16x16x32_bf16 v[120:123], v[168:171], v[192:195], v[120:123]
	v_mfma_f32_16x16x32_bf16 v[108:111], v[160:163], v[202:205], v[108:111]
	v_mfma_f32_16x16x32_bf16 v[104:107], v[168:171], v[202:205], v[104:107]
	v_mfma_f32_16x16x32_bf16 v[92:95], v[160:163], v[210:213], v[92:95]
	v_mfma_f32_16x16x32_bf16 v[88:91], v[168:171], v[210:213], v[88:91]
	v_mfma_f32_16x16x32_bf16 v[76:79], v[160:163], v[218:221], v[76:79]
	v_mfma_f32_16x16x32_bf16 v[72:75], v[168:171], v[218:221], v[72:75]
	v_mfma_f32_16x16x32_bf16 v[116:119], v[172:175], v[188:191], v[116:119]
	v_mfma_f32_16x16x32_bf16 v[112:115], v[180:183], v[188:191], v[112:115]
	v_mfma_f32_16x16x32_bf16 v[100:103], v[172:175], v[198:201], v[100:103]
	v_mfma_f32_16x16x32_bf16 v[96:99], v[180:183], v[198:201], v[96:99]
	v_mfma_f32_16x16x32_bf16 v[84:87], v[172:175], v[206:209], v[84:87]
	v_mfma_f32_16x16x32_bf16 v[80:83], v[180:183], v[206:209], v[80:83]
	v_mfma_f32_16x16x32_bf16 v[68:71], v[172:175], v[214:217], v[68:71]
	v_mfma_f32_16x16x32_bf16 v[64:67], v[180:183], v[214:217], v[64:67]
	v_mfma_f32_16x16x32_bf16 v[116:119], v[176:179], v[192:195], v[116:119]
	v_mfma_f32_16x16x32_bf16 v[112:115], v[184:187], v[192:195], v[112:115]
	v_mfma_f32_16x16x32_bf16 v[100:103], v[176:179], v[202:205], v[100:103]
	v_mfma_f32_16x16x32_bf16 v[96:99], v[184:187], v[202:205], v[96:99]
	v_mfma_f32_16x16x32_bf16 v[84:87], v[176:179], v[210:213], v[84:87]
	v_mfma_f32_16x16x32_bf16 v[80:83], v[184:187], v[210:213], v[80:83]
	v_mfma_f32_16x16x32_bf16 v[68:71], v[176:179], v[218:221], v[68:71]
	v_mfma_f32_16x16x32_bf16 v[64:67], v[184:187], v[218:221], v[64:67]
	s_barrier
	s_add_i32 s4, s33, s47
	v_lshl_add_u64 v[152:153], v[152:153], 0, s[34:35]
	s_mov_b32 m0, s4
	ds_read_b128 v[188:191], v158 offset:49152
	ds_read_b128 v[192:195], v158 offset:50176
	ds_read_b128 v[198:201], v158 offset:51200
	ds_read_b128 v[202:205], v158 offset:52224
	ds_read_b128 v[206:209], v158 offset:53248
	ds_read_b128 v[210:213], v158 offset:54272
	ds_read_b128 v[214:217], v158 offset:55296
	ds_read_b128 v[218:221], v158 offset:56320
	global_load_lds_dwordx4 v[152:153], off
	s_add_i32 m0, s4, 0x2000
	s_add_u32 s4, s14, 0x40080
	v_lshl_add_u64 v[152:153], v[222:223], 0, s[34:35]
	s_addc_u32 s5, s15, 0
	s_add_i32 s14, s40, s47
	global_load_lds_dwordx4 v[152:153], off
	v_lshl_add_u64 v[152:153], s[4:5], 0, v[130:131]
	s_mov_b32 m0, s14
	s_nop 0
	global_load_lds_dwordx4 v[152:153], off
	v_lshl_add_u64 v[152:153], s[4:5], 0, v[134:135]
	s_add_i32 m0, s14, 0x2000
	s_nop 0
	global_load_lds_dwordx4 v[152:153], off
	v_lshl_add_u64 v[152:153], v[224:225], 0, s[34:35]
	s_mov_b32 m0, s68
	s_nop 0
	global_load_lds_dwordx4 v[152:153], off
	v_lshl_add_u64 v[152:153], v[226:227], 0, s[34:35]
	s_mov_b32 m0, s69
	s_nop 0
	global_load_lds_dwordx4 v[152:153], off
	s_waitcnt vmcnt(8)
	s_waitcnt lgkmcnt(0)
	s_barrier
	s_waitcnt lgkmcnt(0)
	v_mfma_f32_16x16x32_bf16 v[60:63], v[148:151], v[188:191], v[60:63]
	v_mfma_f32_16x16x32_bf16 v[56:59], v[164:167], v[188:191], v[56:59]
	v_mfma_f32_16x16x32_bf16 v[44:47], v[148:151], v[198:201], v[44:47]
	v_mfma_f32_16x16x32_bf16 v[40:43], v[164:167], v[198:201], v[40:43]
	v_mfma_f32_16x16x32_bf16 v[28:31], v[148:151], v[206:209], v[28:31]
	v_mfma_f32_16x16x32_bf16 v[24:27], v[164:167], v[206:209], v[24:27]
	v_mfma_f32_16x16x32_bf16 v[12:15], v[148:151], v[214:217], v[12:15]
	v_mfma_f32_16x16x32_bf16 v[8:11], v[164:167], v[214:217], v[8:11]
	v_mfma_f32_16x16x32_bf16 v[60:63], v[160:163], v[192:195], v[60:63]
	v_mfma_f32_16x16x32_bf16 v[56:59], v[168:171], v[192:195], v[56:59]
	v_mfma_f32_16x16x32_bf16 v[44:47], v[160:163], v[202:205], v[44:47]
	v_mfma_f32_16x16x32_bf16 v[40:43], v[168:171], v[202:205], v[40:43]
	v_mfma_f32_16x16x32_bf16 v[28:31], v[160:163], v[210:213], v[28:31]
	v_mfma_f32_16x16x32_bf16 v[24:27], v[168:171], v[210:213], v[24:27]
	v_mfma_f32_16x16x32_bf16 v[12:15], v[160:163], v[218:221], v[12:15]
	v_mfma_f32_16x16x32_bf16 v[8:11], v[168:171], v[218:221], v[8:11]
	v_mfma_f32_16x16x32_bf16 v[52:55], v[172:175], v[188:191], v[52:55]
	v_mfma_f32_16x16x32_bf16 v[48:51], v[180:183], v[188:191], v[48:51]
	v_mfma_f32_16x16x32_bf16 v[36:39], v[172:175], v[198:201], v[36:39]
	v_mfma_f32_16x16x32_bf16 v[32:35], v[180:183], v[198:201], v[32:35]
	v_mfma_f32_16x16x32_bf16 v[20:23], v[172:175], v[206:209], v[20:23]
	v_mfma_f32_16x16x32_bf16 v[16:19], v[180:183], v[206:209], v[16:19]
	v_mfma_f32_16x16x32_bf16 v[4:7], v[172:175], v[214:217], v[4:7]
	v_mfma_f32_16x16x32_bf16 v[0:3], v[180:183], v[214:217], v[0:3]
	v_mfma_f32_16x16x32_bf16 v[52:55], v[176:179], v[192:195], v[52:55]
	v_mfma_f32_16x16x32_bf16 v[48:51], v[184:187], v[192:195], v[48:51]
	v_mfma_f32_16x16x32_bf16 v[36:39], v[176:179], v[202:205], v[36:39]
	v_mfma_f32_16x16x32_bf16 v[32:35], v[184:187], v[202:205], v[32:35]
	v_mfma_f32_16x16x32_bf16 v[20:23], v[176:179], v[210:213], v[20:23]
	v_mfma_f32_16x16x32_bf16 v[16:19], v[184:187], v[210:213], v[16:19]
	v_mfma_f32_16x16x32_bf16 v[4:7], v[176:179], v[218:221], v[4:7]
	v_mfma_f32_16x16x32_bf16 v[0:3], v[184:187], v[218:221], v[0:3]
	s_barrier
	s_add_i32 s59, s59, 2
	s_add_u32 s51, s51, 0x100
	s_addc_u32 s58, s58, 0
	s_add_u32 s8, s8, 0x100
	s_addc_u32 s9, s9, 0
	s_cmp_gt_u32 s59, 13
	s_cbranch_scc0 .LBB0_129
	s_and_b64 vcc, exec, s[36:37]
	s_cbranch_vccz .LBB0_132
	s_barrier

.LBB0_296:
	s_setprio 0
	s_cmp_gt_i32 s77, 3
	s_cselect_b64 s[46:47], -1, 0
	s_and_b64 s[4:5], s[20:21], s[46:47]
	s_andn2_b64 vcc, exec, s[4:5]
	s_cbranch_vccnz .LBB0_342
	s_waitcnt vmcnt(0)
	s_waitcnt vmcnt(0) lgkmcnt(0)
	s_barrier
	s_and_saveexec_b64 s[48:49], s[82:83]
	s_cbranch_execz .LBB0_341
	s_add_i32 s3, 0, 0x20000
	v_mov_b32_e32 v0, s3
	s_waitcnt vmcnt(0) expcnt(0) lgkmcnt(0)
	ds_read_b32 v2, v0
	s_add_i32 s3, 0, 0x20004
	v_mov_b32_e32 v0, s3
	ds_read_b32 v0, v0
	s_waitcnt lgkmcnt(1)
	v_cmp_ne_u32_e32 vcc, 0, v2
	s_cbranch_vccnz .LBB0_312
	s_add_u32 s6, s42, 0x51fda00
	s_addc_u32 s7, s43, 0
	s_add_u32 s10, s42, 0x51fdc00
	s_addc_u32 s11, s43, 0
	s_add_u32 s12, s42, 0x51fdd00
	s_addc_u32 s13, s43, 0
	s_add_u32 s14, s42, 0x51fde00
	s_addc_u32 s15, s43, 0
	s_add_u32 s16, s42, 0x51fdf00
	s_addc_u32 s17, s43, 0
	s_add_u32 s18, s42, 0x51fe000
	s_addc_u32 s19, s43, 0
	s_add_u32 s20, s42, 0x51fe100
	s_addc_u32 s21, s43, 0
	s_add_u32 s22, s42, 0x51fe200
	s_addc_u32 s23, s43, 0
	s_add_u32 s24, s42, 0x51fe300
	s_addc_u32 s25, s43, 0
	s_add_u32 s26, s42, 0x51fe400
	s_addc_u32 s27, s43, 0
	s_add_u32 s28, s42, 0x51fe500
	s_addc_u32 s29, s43, 0
	s_add_u32 s30, s42, 0x51fe600
	s_addc_u32 s31, s43, 0
	s_add_u32 s34, s42, 0x51fe700
	s_addc_u32 s35, s43, 0
	s_add_u32 s36, s42, 0x51fe800
	s_addc_u32 s37, s43, 0
	s_load_dwordx2 s[4:5], s[80:81], 0x4
	s_add_u32 s40, s42, 0x51fe900
	s_addc_u32 s41, s43, 0
	s_add_u32 s44, s42, 0x51fea00
	s_addc_u32 s45, s43, 0
	s_add_u32 s50, s42, 0x51feb00
	s_waitcnt lgkmcnt(0)
	s_mul_i32 s3, s4, s38
	s_addc_u32 s51, s43, 0
	s_mul_i32 s3, s3, s5
	s_mov_b32 s4, 1
	s_mov_b64 s[8:9], 0
	v_mov_b64_e32 v[0:1], s[10:11]
	v_mov_b64_e32 v[2:3], s[12:13]
	v_mov_b64_e32 v[4:5], s[14:15]
	v_mov_b64_e32 v[6:7], s[16:17]
	v_mov_b64_e32 v[8:9], s[18:19]
	v_mov_b64_e32 v[10:11], s[20:21]
	v_mov_b64_e32 v[12:13], s[22:23]
	v_mov_b64_e32 v[14:15], s[24:25]
	v_mov_b64_e32 v[16:17], s[26:27]
	v_mov_b64_e32 v[18:19], s[28:29]
	v_mov_b64_e32 v[20:21], s[30:31]
	v_mov_b64_e32 v[22:23], s[34:35]
	v_mov_b64_e32 v[24:25], s[36:37]
	v_mov_b64_e32 v[26:27], s[40:41]
	v_mov_b64_e32 v[28:29], s[44:45]
	v_mov_b64_e32 v[30:31], s[50:51]
	s_branch .LBB0_302

.LBB0_416:
	s_cmp_lt_i32 s76, 5
	s_cselect_b64 s[20:21], -1, 0
	s_and_b64 s[4:5], s[20:21], s[46:47]
	s_andn2_b64 vcc, exec, s[4:5]
	v_bfe_u32 v222, v196, 2, 4
	s_cbranch_vccnz .LBB0_451
	s_cmpk_lt_i32 s2, 0x14a0
	s_cselect_b64 s[12:13], -1, 0
	s_cmpk_gt_i32 s2, 0x149f
	s_mov_b64 s[8:9], s[0:1]
	v_readfirstlane_b32 s34, v196
	s_waitcnt vmcnt(0) lgkmcnt(0)
	s_barrier
	s_cbranch_scc1 .LBB0_419
	s_lshr_b32 s99, s34, 8
	s_cmp_eq_u32 s99, 1
	s_cbranch_scc0 .Lprio_p4
	s_setprio 1
.Lprio_p4:
	s_ashr_i32 s3, s2, 31
	s_lshr_b32 s3, s3, 29
	s_add_i32 s3, s2, s3
	s_ashr_i32 s4, s3, 3
	s_and_b32 s3, s3, -8
	s_sub_i32 s3, s2, s3
	s_cmp_lt_i32 s3, 0
	s_movk_i32 s5, 0x295
	s_cselect_b32 s5, s5, 0x294
	s_mul_i32 s3, s3, s5
	s_add_i32 s3, s3, s4
	s_mul_hi_i32 s4, s3, 0x66666667
	s_lshr_b32 s5, s4, 31
	s_ashr_i32 s4, s4, 6
	s_add_i32 s4, s4, s5
	s_lshl_b32 s5, s4, 3
	s_mulk_i32 s4, 0xa0
	s_sub_i32 s3, s3, s4
	s_sext_i32_i16 s4, s3
	s_bfe_u32 s4, s4, 0x3001c
	s_add_i32 s4, s3, s4
	s_sext_i32_i16 s6, s4
	s_and_b32 s4, s4, 0xfff8
	s_sub_i32 s3, s3, s4
	s_ashr_i32 s10, s6, 3
	s_sext_i32_i16 s3, s3
	s_and_b32 s4, s10, -4
	s_add_i32 s90, s5, s3
	s_ashr_i32 s5, s4, 31
	s_lshl_b64 s[6:7], s[4:5], 7
	s_andn2_b64 vcc, exec, s[12:13]
	s_cbranch_vccz .LBB0_420
	s_branch .LBB0_451

.LBB0_430:
	s_add_u32 s33, s14, s49
	s_addc_u32 s40, s15, 0
	s_add_u32 s41, s33, 0x100
	s_addc_u32 s44, s40, 0
	s_and_b64 s[4:5], s[54:55], exec
	s_cselect_b32 s59, s51, s44
	s_cselect_b32 s58, s50, s41
	s_add_u32 s4, s12, s49
	s_addc_u32 s5, s13, 0
	s_add_u32 s41, s4, 0x100
	s_addc_u32 s44, s5, 0
	s_and_b64 s[4:5], s[54:55], exec
	s_cselect_b32 s61, s11, s44
	s_cselect_b32 s60, s47, s41
	s_add_u32 s64, s33, 0x50080
	s_addc_u32 s65, s40, 0
	s_add_i32 vcc_lo, s86, s67
	ds_read_b128 v[64:67], v211
	ds_read_b128 v[68:71], v211 offset:1024
	ds_read_b128 v[72:75], v211 offset:2048
	ds_read_b128 v[84:87], v211 offset:3072
	ds_read_b128 v[88:91], v212
	ds_read_b128 v[92:95], v212 offset:1024
	ds_read_b128 v[172:175], v212 offset:2048
	ds_read_b128 v[176:179], v212 offset:3072
	s_add_i32 m0, s70, 0xc000
	s_add_i32 s4, s70, 0xe000
	s_add_i32 s94, vcc_lo, 0x2000
	s_add_u32 s62, s60, 0x10000
	s_addc_u32 s63, s61, 0
	s_add_i32 vcc_hi, s87, s67
	s_add_i32 s33, vcc_hi, 0x2000
	s_add_i32 s97, 0, 0x18000
	s_add_i32 s96, 0, 0x1c000
	s_add_u32 s56, s58, 0x50000
	s_addc_u32 s57, s59, 0
	s_add_i32 s93, s97, s67
	s_add_i32 s91, s93, 0x2000
	s_add_u32 s54, s60, 0x10080
	s_addc_u32 s55, s61, 0
	s_add_i32 s92, s96, s67
	s_add_i32 s49, s92, 0x2000
	v_lshl_add_u64 v[180:181], s[64:65], 0, v[152:153]
	ds_read_b128 v[190:193], v213
	ds_read_b128 v[198:201], v213 offset:1024
	ds_read_b128 v[202:205], v213 offset:2048
	ds_read_b128 v[216:219], v213 offset:3072
	ds_read_b128 v[224:227], v213 offset:4096
	ds_read_b128 v[228:231], v213 offset:5120
	ds_read_b128 v[232:235], v213 offset:6144
	ds_read_b128 v[236:239], v213 offset:7168
	global_load_lds_dwordx4 v[180:181], off
	v_lshl_add_u64 v[180:181], s[64:65], 0, v[156:157]
	s_mov_b32 m0, s4
	s_nop 0
	global_load_lds_dwordx4 v[180:181], off
	s_waitcnt vmcnt(8)
	s_waitcnt lgkmcnt(0)
	s_barrier
	s_waitcnt lgkmcnt(0)
	v_mfma_f32_16x16x32_bf16 v[148:151], v[64:67], v[190:193], v[148:151]
	v_mfma_f32_16x16x32_bf16 v[144:147], v[72:75], v[190:193], v[144:147]
	v_mfma_f32_16x16x32_bf16 v[140:143], v[64:67], v[202:205], v[140:143]
	v_mfma_f32_16x16x32_bf16 v[136:139], v[72:75], v[202:205], v[136:139]
	v_mfma_f32_16x16x32_bf16 v[132:135], v[64:67], v[224:227], v[132:135]
	v_mfma_f32_16x16x32_bf16 v[128:131], v[72:75], v[224:227], v[128:131]
	v_mfma_f32_16x16x32_bf16 v[124:127], v[64:67], v[232:235], v[124:127]
	v_mfma_f32_16x16x32_bf16 v[120:123], v[72:75], v[232:235], v[120:123]
	v_mfma_f32_16x16x32_bf16 v[148:151], v[68:71], v[198:201], v[148:151]
	v_mfma_f32_16x16x32_bf16 v[144:147], v[84:87], v[198:201], v[144:147]
	v_mfma_f32_16x16x32_bf16 v[140:143], v[68:71], v[216:219], v[140:143]
	v_mfma_f32_16x16x32_bf16 v[136:139], v[84:87], v[216:219], v[136:139]
	v_mfma_f32_16x16x32_bf16 v[132:135], v[68:71], v[228:231], v[132:135]
	v_mfma_f32_16x16x32_bf16 v[128:131], v[84:87], v[228:231], v[128:131]
	v_mfma_f32_16x16x32_bf16 v[124:127], v[68:71], v[236:239], v[124:127]
	v_mfma_f32_16x16x32_bf16 v[120:123], v[84:87], v[236:239], v[120:123]
	v_mfma_f32_16x16x32_bf16 v[116:119], v[88:91], v[190:193], v[116:119]
	v_mfma_f32_16x16x32_bf16 v[112:115], v[172:175], v[190:193], v[112:115]
	v_mfma_f32_16x16x32_bf16 v[108:111], v[88:91], v[202:205], v[108:111]
	v_mfma_f32_16x16x32_bf16 v[104:107], v[172:175], v[202:205], v[104:107]
	v_mfma_f32_16x16x32_bf16 v[100:103], v[88:91], v[224:227], v[100:103]
	v_mfma_f32_16x16x32_bf16 v[96:99], v[172:175], v[224:227], v[96:99]
	v_mfma_f32_16x16x32_bf16 v[80:83], v[88:91], v[232:235], v[80:83]
	v_mfma_f32_16x16x32_bf16 v[76:79], v[172:175], v[232:235], v[76:79]
	v_mfma_f32_16x16x32_bf16 v[116:119], v[92:95], v[198:201], v[116:119]
	v_mfma_f32_16x16x32_bf16 v[112:115], v[176:179], v[198:201], v[112:115]
	v_mfma_f32_16x16x32_bf16 v[108:111], v[92:95], v[216:219], v[108:111]
	v_mfma_f32_16x16x32_bf16 v[104:107], v[176:179], v[216:219], v[104:107]
	v_mfma_f32_16x16x32_bf16 v[100:103], v[92:95], v[228:231], v[100:103]
	v_mfma_f32_16x16x32_bf16 v[96:99], v[176:179], v[228:231], v[96:99]
	v_mfma_f32_16x16x32_bf16 v[80:83], v[92:95], v[236:239], v[80:83]
	v_mfma_f32_16x16x32_bf16 v[76:79], v[176:179], v[236:239], v[76:79]
	s_barrier
	s_mov_b32 m0, vcc_lo
	v_lshl_add_u64 v[180:181], s[60:61], 0, v[154:155]
	ds_read_b128 v[190:193], v213 offset:16384
	ds_read_b128 v[198:201], v213 offset:17408
	ds_read_b128 v[202:205], v213 offset:18432
	ds_read_b128 v[216:219], v213 offset:19456
	ds_read_b128 v[224:227], v213 offset:20480
	ds_read_b128 v[228:231], v213 offset:21504
	ds_read_b128 v[232:235], v213 offset:22528
	ds_read_b128 v[236:239], v213 offset:23552
	global_load_lds_dwordx4 v[180:181], off
	v_lshl_add_u64 v[194:195], s[60:61], 0, v[158:159]
	s_mov_b32 m0, s94
	v_lshl_add_u64 v[206:207], s[62:63], 0, v[154:155]
	global_load_lds_dwordx4 v[194:195], off
	s_mov_b32 m0, vcc_hi
	v_lshl_add_u64 v[220:221], s[58:59], 0, v[156:157]
	global_load_lds_dwordx4 v[206:207], off
	v_lshl_add_u64 v[206:207], s[62:63], 0, v[158:159]
	s_mov_b32 m0, s33
	s_nop 0
	global_load_lds_dwordx4 v[206:207], off
	v_lshl_add_u64 v[206:207], s[58:59], 0, v[152:153]
	s_mov_b32 m0, s70
	s_nop 0
	global_load_lds_dwordx4 v[206:207], off
	s_mov_b32 m0, s71
	s_nop 0
	global_load_lds_dwordx4 v[220:221], off
	s_waitcnt vmcnt(8)
	s_waitcnt lgkmcnt(0)
	s_barrier
	s_waitcnt lgkmcnt(0)
	v_mfma_f32_16x16x32_bf16 v[60:63], v[64:67], v[190:193], v[60:63]
	v_mfma_f32_16x16x32_bf16 v[56:59], v[72:75], v[190:193], v[56:59]
	v_mfma_f32_16x16x32_bf16 v[52:55], v[64:67], v[202:205], v[52:55]
	v_mfma_f32_16x16x32_bf16 v[48:51], v[72:75], v[202:205], v[48:51]
	v_mfma_f32_16x16x32_bf16 v[44:47], v[64:67], v[224:227], v[44:47]
	v_mfma_f32_16x16x32_bf16 v[40:43], v[72:75], v[224:227], v[40:43]
	v_mfma_f32_16x16x32_bf16 v[36:39], v[64:67], v[232:235], v[36:39]
	v_mfma_f32_16x16x32_bf16 v[32:35], v[72:75], v[232:235], v[32:35]
	v_mfma_f32_16x16x32_bf16 v[60:63], v[68:71], v[198:201], v[60:63]
	v_mfma_f32_16x16x32_bf16 v[56:59], v[84:87], v[198:201], v[56:59]
	v_mfma_f32_16x16x32_bf16 v[52:55], v[68:71], v[216:219], v[52:55]
	v_mfma_f32_16x16x32_bf16 v[48:51], v[84:87], v[216:219], v[48:51]
	v_mfma_f32_16x16x32_bf16 v[44:47], v[68:71], v[228:231], v[44:47]
	v_mfma_f32_16x16x32_bf16 v[40:43], v[84:87], v[228:231], v[40:43]
	v_mfma_f32_16x16x32_bf16 v[36:39], v[68:71], v[236:239], v[36:39]
	v_mfma_f32_16x16x32_bf16 v[32:35], v[84:87], v[236:239], v[32:35]
	v_mfma_f32_16x16x32_bf16 v[28:31], v[88:91], v[190:193], v[28:31]
	v_mfma_f32_16x16x32_bf16 v[24:27], v[172:175], v[190:193], v[24:27]
	v_mfma_f32_16x16x32_bf16 v[20:23], v[88:91], v[202:205], v[20:23]
	v_mfma_f32_16x16x32_bf16 v[16:19], v[172:175], v[202:205], v[16:19]
	v_mfma_f32_16x16x32_bf16 v[12:15], v[88:91], v[224:227], v[12:15]
	v_mfma_f32_16x16x32_bf16 v[8:11], v[172:175], v[224:227], v[8:11]
	v_mfma_f32_16x16x32_bf16 v[4:7], v[88:91], v[232:235], v[4:7]
	v_mfma_f32_16x16x32_bf16 v[0:3], v[172:175], v[232:235], v[0:3]
	v_mfma_f32_16x16x32_bf16 v[28:31], v[92:95], v[198:201], v[28:31]
	v_mfma_f32_16x16x32_bf16 v[24:27], v[176:179], v[198:201], v[24:27]
	v_mfma_f32_16x16x32_bf16 v[20:23], v[92:95], v[216:219], v[20:23]
	v_mfma_f32_16x16x32_bf16 v[16:19], v[176:179], v[216:219], v[16:19]
	v_mfma_f32_16x16x32_bf16 v[12:15], v[92:95], v[228:231], v[12:15]
	v_mfma_f32_16x16x32_bf16 v[8:11], v[176:179], v[228:231], v[8:11]
	v_mfma_f32_16x16x32_bf16 v[4:7], v[92:95], v[236:239], v[4:7]
	v_mfma_f32_16x16x32_bf16 v[0:3], v[176:179], v[236:239], v[0:3]
	s_barrier
	v_add_u32_e32 v84, s97, v210
	v_add_u32_e32 v176, s96, v210
	ds_read_b128 v[64:67], v84
	ds_read_b128 v[68:71], v84 offset:1024
	ds_read_b128 v[72:75], v84 offset:2048
	ds_read_b128 v[84:87], v84 offset:3072
	ds_read_b128 v[88:91], v176
	ds_read_b128 v[92:95], v176 offset:1024
	ds_read_b128 v[172:175], v176 offset:2048
	ds_read_b128 v[176:179], v176 offset:3072
	s_mov_b32 m0, s72
	v_lshl_add_u64 v[240:241], s[56:57], 0, v[152:153]
	ds_read_b128 v[190:193], v213 offset:32768
	ds_read_b128 v[198:201], v213 offset:33792
	ds_read_b128 v[202:205], v213 offset:34816
	ds_read_b128 v[216:219], v213 offset:35840
	ds_read_b128 v[224:227], v213 offset:36864
	ds_read_b128 v[228:231], v213 offset:37888
	ds_read_b128 v[232:235], v213 offset:38912
	ds_read_b128 v[236:239], v213 offset:39936
	global_load_lds_dwordx4 v[240:241], off
	v_lshl_add_u64 v[240:241], s[56:57], 0, v[156:157]
	s_mov_b32 m0, s73
	s_nop 0
	global_load_lds_dwordx4 v[240:241], off
	s_waitcnt vmcnt(8)
	s_waitcnt lgkmcnt(0)
	s_barrier
	s_waitcnt lgkmcnt(0)
	v_mfma_f32_16x16x32_bf16 v[148:151], v[64:67], v[190:193], v[148:151]
	v_mfma_f32_16x16x32_bf16 v[144:147], v[72:75], v[190:193], v[144:147]
	v_mfma_f32_16x16x32_bf16 v[140:143], v[64:67], v[202:205], v[140:143]
	v_mfma_f32_16x16x32_bf16 v[136:139], v[72:75], v[202:205], v[136:139]
	v_mfma_f32_16x16x32_bf16 v[132:135], v[64:67], v[224:227], v[132:135]
	v_mfma_f32_16x16x32_bf16 v[128:131], v[72:75], v[224:227], v[128:131]
	v_mfma_f32_16x16x32_bf16 v[124:127], v[64:67], v[232:235], v[124:127]
	v_mfma_f32_16x16x32_bf16 v[120:123], v[72:75], v[232:235], v[120:123]
	v_mfma_f32_16x16x32_bf16 v[148:151], v[68:71], v[198:201], v[148:151]
	v_mfma_f32_16x16x32_bf16 v[144:147], v[84:87], v[198:201], v[144:147]
	v_mfma_f32_16x16x32_bf16 v[140:143], v[68:71], v[216:219], v[140:143]
	v_mfma_f32_16x16x32_bf16 v[136:139], v[84:87], v[216:219], v[136:139]
	v_mfma_f32_16x16x32_bf16 v[132:135], v[68:71], v[228:231], v[132:135]
	v_mfma_f32_16x16x32_bf16 v[128:131], v[84:87], v[228:231], v[128:131]
	v_mfma_f32_16x16x32_bf16 v[124:127], v[68:71], v[236:239], v[124:127]
	v_mfma_f32_16x16x32_bf16 v[120:123], v[84:87], v[236:239], v[120:123]
	v_mfma_f32_16x16x32_bf16 v[116:119], v[88:91], v[190:193], v[116:119]
	v_mfma_f32_16x16x32_bf16 v[112:115], v[172:175], v[190:193], v[112:115]
	v_mfma_f32_16x16x32_bf16 v[108:111], v[88:91], v[202:205], v[108:111]
	v_mfma_f32_16x16x32_bf16 v[104:107], v[172:175], v[202:205], v[104:107]
	v_mfma_f32_16x16x32_bf16 v[100:103], v[88:91], v[224:227], v[100:103]
	v_mfma_f32_16x16x32_bf16 v[96:99], v[172:175], v[224:227], v[96:99]
	v_mfma_f32_16x16x32_bf16 v[80:83], v[88:91], v[232:235], v[80:83]
	v_mfma_f32_16x16x32_bf16 v[76:79], v[172:175], v[232:235], v[76:79]
	v_mfma_f32_16x16x32_bf16 v[116:119], v[92:95], v[198:201], v[116:119]
	v_mfma_f32_16x16x32_bf16 v[112:115], v[176:179], v[198:201], v[112:115]
	v_mfma_f32_16x16x32_bf16 v[108:111], v[92:95], v[216:219], v[108:111]
	v_mfma_f32_16x16x32_bf16 v[104:107], v[176:179], v[216:219], v[104:107]
	v_mfma_f32_16x16x32_bf16 v[100:103], v[92:95], v[228:231], v[100:103]
	v_mfma_f32_16x16x32_bf16 v[96:99], v[176:179], v[228:231], v[96:99]
	v_mfma_f32_16x16x32_bf16 v[80:83], v[92:95], v[236:239], v[80:83]
	v_mfma_f32_16x16x32_bf16 v[76:79], v[176:179], v[236:239], v[76:79]
	s_barrier
	s_mov_b32 m0, s93
	v_lshl_add_u64 v[180:181], v[180:181], 0, s[18:19]
	ds_read_b128 v[190:193], v213 offset:49152
	ds_read_b128 v[198:201], v213 offset:50176
	ds_read_b128 v[202:205], v213 offset:51200
	ds_read_b128 v[216:219], v213 offset:52224
	ds_read_b128 v[224:227], v213 offset:53248
	ds_read_b128 v[228:231], v213 offset:54272
	ds_read_b128 v[232:235], v213 offset:55296
	ds_read_b128 v[236:239], v213 offset:56320
	global_load_lds_dwordx4 v[180:181], off
	v_lshl_add_u64 v[180:181], v[194:195], 0, s[18:19]
	s_mov_b32 m0, s91
	s_nop 0
	global_load_lds_dwordx4 v[180:181], off
	v_lshl_add_u64 v[180:181], s[54:55], 0, v[154:155]
	s_mov_b32 m0, s92
	s_nop 0
	global_load_lds_dwordx4 v[180:181], off
	v_lshl_add_u64 v[180:181], s[54:55], 0, v[158:159]
	s_mov_b32 m0, s49
	s_nop 0
	global_load_lds_dwordx4 v[180:181], off
	v_lshl_add_u64 v[180:181], v[206:207], 0, s[18:19]
	s_mov_b32 m0, s83
	s_nop 0
	global_load_lds_dwordx4 v[180:181], off
	v_lshl_add_u64 v[180:181], v[220:221], 0, s[18:19]
	s_mov_b32 m0, s84
	s_nop 0
	global_load_lds_dwordx4 v[180:181], off
	s_waitcnt vmcnt(8)
	s_waitcnt lgkmcnt(0)
	s_barrier
	s_waitcnt lgkmcnt(0)
	v_mfma_f32_16x16x32_bf16 v[60:63], v[64:67], v[190:193], v[60:63]
	v_mfma_f32_16x16x32_bf16 v[56:59], v[72:75], v[190:193], v[56:59]
	v_mfma_f32_16x16x32_bf16 v[52:55], v[64:67], v[202:205], v[52:55]
	v_mfma_f32_16x16x32_bf16 v[48:51], v[72:75], v[202:205], v[48:51]
	v_mfma_f32_16x16x32_bf16 v[44:47], v[64:67], v[224:227], v[44:47]
	v_mfma_f32_16x16x32_bf16 v[40:43], v[72:75], v[224:227], v[40:43]
	v_mfma_f32_16x16x32_bf16 v[36:39], v[64:67], v[232:235], v[36:39]
	v_mfma_f32_16x16x32_bf16 v[32:35], v[72:75], v[232:235], v[32:35]
	v_mfma_f32_16x16x32_bf16 v[60:63], v[68:71], v[198:201], v[60:63]
	v_mfma_f32_16x16x32_bf16 v[56:59], v[84:87], v[198:201], v[56:59]
	v_mfma_f32_16x16x32_bf16 v[52:55], v[68:71], v[216:219], v[52:55]
	v_mfma_f32_16x16x32_bf16 v[48:51], v[84:87], v[216:219], v[48:51]
	v_mfma_f32_16x16x32_bf16 v[44:47], v[68:71], v[228:231], v[44:47]
	v_mfma_f32_16x16x32_bf16 v[40:43], v[84:87], v[228:231], v[40:43]
	v_mfma_f32_16x16x32_bf16 v[36:39], v[68:71], v[236:239], v[36:39]
	v_mfma_f32_16x16x32_bf16 v[32:35], v[84:87], v[236:239], v[32:35]
	v_mfma_f32_16x16x32_bf16 v[28:31], v[88:91], v[190:193], v[28:31]
	v_mfma_f32_16x16x32_bf16 v[24:27], v[172:175], v[190:193], v[24:27]
	v_mfma_f32_16x16x32_bf16 v[20:23], v[88:91], v[202:205], v[20:23]
	v_mfma_f32_16x16x32_bf16 v[16:19], v[172:175], v[202:205], v[16:19]
	v_mfma_f32_16x16x32_bf16 v[12:15], v[88:91], v[224:227], v[12:15]
	v_mfma_f32_16x16x32_bf16 v[8:11], v[172:175], v[224:227], v[8:11]
	v_mfma_f32_16x16x32_bf16 v[4:7], v[88:91], v[232:235], v[4:7]
	v_mfma_f32_16x16x32_bf16 v[0:3], v[172:175], v[232:235], v[0:3]
	v_mfma_f32_16x16x32_bf16 v[28:31], v[92:95], v[198:201], v[28:31]
	v_mfma_f32_16x16x32_bf16 v[24:27], v[176:179], v[198:201], v[24:27]
	v_mfma_f32_16x16x32_bf16 v[20:23], v[92:95], v[216:219], v[20:23]
	v_mfma_f32_16x16x32_bf16 v[16:19], v[176:179], v[216:219], v[16:19]
	v_mfma_f32_16x16x32_bf16 v[12:15], v[92:95], v[228:231], v[12:15]
	v_mfma_f32_16x16x32_bf16 v[8:11], v[176:179], v[228:231], v[8:11]
	v_mfma_f32_16x16x32_bf16 v[4:7], v[92:95], v[236:239], v[4:7]
	v_mfma_f32_16x16x32_bf16 v[0:3], v[176:179], v[236:239], v[0:3]
	s_barrier
	s_movk_i32 s49, 0x100
	s_andn2_b64 vcc, exec, s[8:9]
	s_mov_b64 s[54:55], -1
	s_mov_b64 s[8:9], 0
	s_cbranch_vccz .LBB0_430
	s_and_b64 vcc, exec, s[34:35]
	s_cbranch_vccz .LBB0_433
	s_barrier

.LBB0_451:
	s_setprio 0
	s_waitcnt lgkmcnt(0)
	s_cmp_gt_i32 s77, 5
	s_cselect_b64 s[46:47], -1, 0
	s_and_b64 s[4:5], s[20:21], s[46:47]
	s_andn2_b64 vcc, exec, s[4:5]
	s_cbranch_vccnz .LBB0_497
	s_waitcnt vmcnt(0)
	s_waitcnt vmcnt(0)
	s_barrier
	s_and_saveexec_b64 s[48:49], s[82:83]
	s_cbranch_execz .LBB0_496
	s_add_i32 s3, 0, 0x20000
	v_mov_b32_e32 v0, s3
	s_waitcnt vmcnt(0) expcnt(0) lgkmcnt(0)
	ds_read_b32 v2, v0
	s_add_i32 s3, 0, 0x20004
	v_mov_b32_e32 v0, s3
	ds_read_b32 v0, v0
	s_waitcnt lgkmcnt(1)
	v_cmp_ne_u32_e32 vcc, 0, v2
	s_cbranch_vccnz .LBB0_467
	s_add_u32 s6, s42, 0x51fda00
	s_addc_u32 s7, s43, 0
	s_add_u32 s10, s42, 0x51fdc00
	s_addc_u32 s11, s43, 0
	s_add_u32 s12, s42, 0x51fdd00
	s_addc_u32 s13, s43, 0
	s_add_u32 s14, s42, 0x51fde00
	s_addc_u32 s15, s43, 0
	s_add_u32 s16, s42, 0x51fdf00
	s_addc_u32 s17, s43, 0
	s_add_u32 s18, s42, 0x51fe000
	s_addc_u32 s19, s43, 0
	s_add_u32 s20, s42, 0x51fe100
	s_addc_u32 s21, s43, 0
	s_add_u32 s22, s42, 0x51fe200
	s_addc_u32 s23, s43, 0
	s_add_u32 s24, s42, 0x51fe300
	s_addc_u32 s25, s43, 0
	s_add_u32 s26, s42, 0x51fe400
	s_addc_u32 s27, s43, 0
	s_add_u32 s28, s42, 0x51fe500
	s_addc_u32 s29, s43, 0
	s_add_u32 s30, s42, 0x51fe600
	s_addc_u32 s31, s43, 0
	s_add_u32 s34, s42, 0x51fe700
	s_addc_u32 s35, s43, 0
	s_add_u32 s36, s42, 0x51fe800
	s_addc_u32 s37, s43, 0
	s_load_dwordx2 s[4:5], s[80:81], 0x4
	s_add_u32 s40, s42, 0x51fe900
	s_addc_u32 s41, s43, 0
	s_add_u32 s44, s42, 0x51fea00
	s_addc_u32 s45, s43, 0
	s_add_u32 s50, s42, 0x51feb00
	s_waitcnt lgkmcnt(0)
	s_mul_i32 s3, s4, s38
	s_addc_u32 s51, s43, 0
	s_mul_i32 s3, s3, s5
	s_mov_b32 s4, 1
	s_mov_b64 s[8:9], 0
	v_mov_b64_e32 v[0:1], s[10:11]
	v_mov_b64_e32 v[2:3], s[12:13]
	v_mov_b64_e32 v[4:5], s[14:15]
	v_mov_b64_e32 v[6:7], s[16:17]
	v_mov_b64_e32 v[8:9], s[18:19]
	v_mov_b64_e32 v[10:11], s[20:21]
	v_mov_b64_e32 v[12:13], s[22:23]
	v_mov_b64_e32 v[14:15], s[24:25]
	v_mov_b64_e32 v[16:17], s[26:27]
	v_mov_b64_e32 v[18:19], s[28:29]
	v_mov_b64_e32 v[20:21], s[30:31]
	v_mov_b64_e32 v[22:23], s[34:35]
	v_mov_b64_e32 v[24:25], s[36:37]
	v_mov_b64_e32 v[26:27], s[40:41]
	v_mov_b64_e32 v[28:29], s[44:45]
	v_mov_b64_e32 v[30:31], s[50:51]
	s_branch .LBB0_457

.LBB0_567:
	s_cmp_lt_i32 s76, 8
	s_cselect_b64 s[12:13], -1, 0
	s_cmp_gt_i32 s77, 7
	s_cselect_b64 s[4:5], -1, 0
	s_and_b64 s[4:5], s[12:13], s[4:5]
	s_andn2_b64 vcc, exec, s[4:5]
	v_bfe_u32 v223, v196, 2, 2
	s_cbranch_vccnz .LBB0_692
	s_cmpk_lt_i32 s2, 0x400
	s_cselect_b64 s[8:9], -1, 0
	s_cmpk_gt_i32 s2, 0x3ff
	s_mov_b64 s[6:7], s[0:1]
	v_readfirstlane_b32 s20, v196
	s_waitcnt vmcnt(0) lgkmcnt(0)
	s_barrier
	s_cbranch_scc1 .LBB0_570
	s_lshr_b32 s99, s20, 8
	s_cmp_eq_u32 s99, 1
	s_cbranch_scc0 .Lprio_p7
	s_setprio 1
.Lprio_p7:
	s_ashr_i32 s3, s2, 31
	s_lshr_b32 s3, s3, 29
	s_add_i32 s3, s2, s3
	s_ashr_i32 s4, s3, 3
	s_and_b32 s3, s3, -8
	s_sub_i32 s3, s2, s3
	s_lshl_b32 s10, s3, 7
	s_mul_i32 s5, s3, 0x81
	s_cmp_lt_i32 s3, 0
	s_cselect_b32 s3, s5, s10
	s_add_i32 s3, s3, s4
	s_ashr_i32 s4, s3, 31
	s_lshr_b32 s4, s4, 27
	s_add_i32 s4, s3, s4
	s_ashr_i32 s5, s4, 5
	s_andn2_b32 s4, s4, 31
	s_sub_i32 s3, s3, s4
	s_bfe_i32 s4, s3, 0x80000
	s_bfe_u32 s4, s4, 0x3000c
	s_add_i32 s4, s3, s4
	s_bfe_i32 s10, s4, 0x80000
	s_and_b32 s4, s4, 0xf8
	s_sub_i32 s3, s3, s4
	s_lshl_b32 s5, s5, 3
	s_sext_i32_i16 s10, s10
	s_sext_i32_i8 s3, s3
	s_add_i32 s65, s5, s3
	s_ashr_i32 s64, s10, 3

.LBB0_587:
	v_add_u32_e32 v1, s56, v226
	ds_read_b128 v[132:135], v1
	ds_read_b128 v[136:139], v1 offset:1024
	ds_read_b128 v[140:143], v1 offset:2048
	ds_read_b128 v[144:147], v1 offset:3072
	v_add_u32_e32 v1, s57, v226
	ds_read_b128 v[148:151], v1
	ds_read_b128 v[152:155], v1 offset:1024
	ds_read_b128 v[156:159], v1 offset:2048
	ds_read_b128 v[160:163], v1 offset:3072
	s_add_i32 s70, s4, 2
	s_add_u32 s5, s8, 0xffe60080
	s_addc_u32 s10, s9, -1
	s_cmp_eq_u32 s27, s4
	s_cselect_b32 s35, s29, s10
	s_cselect_b32 s34, s28, s5
	s_cselect_b32 s11, s31, s69
	s_cselect_b32 s10, s30, s68
	v_lshl_add_u64 v[2:3], s[8:9], 0, v[208:209]
	s_add_i32 m0, s47, 0xc000
	ds_read_b128 v[164:167], v227
	ds_read_b128 v[168:171], v227 offset:1024
	ds_read_b128 v[172:175], v227 offset:2048
	ds_read_b128 v[176:179], v227 offset:3072
	ds_read_b128 v[180:183], v227 offset:4096
	ds_read_b128 v[184:187], v227 offset:5120
	ds_read_b128 v[188:191], v227 offset:6144
	ds_read_b128 v[192:195], v227 offset:7168
	global_load_lds_dwordx4 v[2:3], off
	v_lshl_add_u64 v[2:3], s[8:9], 0, v[206:207]
	s_add_i32 m0, s47, 0xe000
	s_nop 0
	global_load_lds_dwordx4 v[2:3], off
	s_waitcnt vmcnt(8)
	s_waitcnt lgkmcnt(0)
	s_barrier
	s_waitcnt lgkmcnt(0)
	v_mfma_f32_16x16x32_bf16 v[128:131], v[132:135], v[164:167], v[128:131]
	v_mfma_f32_16x16x32_bf16 v[124:127], v[140:143], v[164:167], v[124:127]
	v_mfma_f32_16x16x32_bf16 v[120:123], v[132:135], v[172:175], v[120:123]
	v_mfma_f32_16x16x32_bf16 v[116:119], v[140:143], v[172:175], v[116:119]
	v_mfma_f32_16x16x32_bf16 v[112:115], v[132:135], v[180:183], v[112:115]
	v_mfma_f32_16x16x32_bf16 v[108:111], v[140:143], v[180:183], v[108:111]
	v_mfma_f32_16x16x32_bf16 v[104:107], v[132:135], v[188:191], v[104:107]
	v_mfma_f32_16x16x32_bf16 v[100:103], v[140:143], v[188:191], v[100:103]
	v_mfma_f32_16x16x32_bf16 v[128:131], v[136:139], v[168:171], v[128:131]
	v_mfma_f32_16x16x32_bf16 v[124:127], v[144:147], v[168:171], v[124:127]
	v_mfma_f32_16x16x32_bf16 v[120:123], v[136:139], v[176:179], v[120:123]
	v_mfma_f32_16x16x32_bf16 v[116:119], v[144:147], v[176:179], v[116:119]
	v_mfma_f32_16x16x32_bf16 v[112:115], v[136:139], v[184:187], v[112:115]
	v_mfma_f32_16x16x32_bf16 v[108:111], v[144:147], v[184:187], v[108:111]
	v_mfma_f32_16x16x32_bf16 v[104:107], v[136:139], v[192:195], v[104:107]
	v_mfma_f32_16x16x32_bf16 v[100:103], v[144:147], v[192:195], v[100:103]
	v_mfma_f32_16x16x32_bf16 v[96:99], v[148:151], v[164:167], v[96:99]
	v_mfma_f32_16x16x32_bf16 v[92:95], v[156:159], v[164:167], v[92:95]
	v_mfma_f32_16x16x32_bf16 v[88:91], v[148:151], v[172:175], v[88:91]
	v_mfma_f32_16x16x32_bf16 v[84:87], v[156:159], v[172:175], v[84:87]
	v_mfma_f32_16x16x32_bf16 v[80:83], v[148:151], v[180:183], v[80:83]
	v_mfma_f32_16x16x32_bf16 v[76:79], v[156:159], v[180:183], v[76:79]
	v_mfma_f32_16x16x32_bf16 v[72:75], v[148:151], v[188:191], v[72:75]
	v_mfma_f32_16x16x32_bf16 v[68:71], v[156:159], v[188:191], v[68:71]
	v_mfma_f32_16x16x32_bf16 v[96:99], v[152:155], v[168:171], v[96:99]
	v_mfma_f32_16x16x32_bf16 v[92:95], v[160:163], v[168:171], v[92:95]
	v_mfma_f32_16x16x32_bf16 v[88:91], v[152:155], v[176:179], v[88:91]
	v_mfma_f32_16x16x32_bf16 v[84:87], v[160:163], v[176:179], v[84:87]
	v_mfma_f32_16x16x32_bf16 v[80:83], v[152:155], v[184:187], v[80:83]
	v_mfma_f32_16x16x32_bf16 v[76:79], v[160:163], v[184:187], v[76:79]
	v_mfma_f32_16x16x32_bf16 v[72:75], v[152:155], v[192:195], v[72:75]
	v_mfma_f32_16x16x32_bf16 v[68:71], v[160:163], v[192:195], v[68:71]
	s_barrier
	s_add_i32 s4, s56, s46
	v_lshl_add_u64 v[214:215], s[10:11], 0, v[200:201]
	s_mov_b32 m0, s4
	ds_read_b128 v[164:167], v227 offset:16384
	ds_read_b128 v[168:171], v227 offset:17408
	ds_read_b128 v[172:175], v227 offset:18432
	ds_read_b128 v[176:179], v227 offset:19456
	ds_read_b128 v[180:183], v227 offset:20480
	ds_read_b128 v[184:187], v227 offset:21504
	ds_read_b128 v[188:191], v227 offset:22528
	ds_read_b128 v[192:195], v227 offset:23552
	global_load_lds_dwordx4 v[214:215], off
	s_add_i32 m0, s4, 0x2000
	s_add_u32 s4, s10, 0x90000
	v_lshl_add_u64 v[216:217], s[10:11], 0, v[204:205]
	s_addc_u32 s5, s11, 0
	s_add_i32 s33, s57, s46
	global_load_lds_dwordx4 v[216:217], off
	v_lshl_add_u64 v[2:3], s[4:5], 0, v[200:201]
	s_mov_b32 m0, s33
	v_lshl_add_u64 v[218:219], s[34:35], 0, v[198:199]
	global_load_lds_dwordx4 v[2:3], off
	v_lshl_add_u64 v[2:3], s[4:5], 0, v[204:205]
	s_add_i32 m0, s33, 0x2000
	v_lshl_add_u64 v[220:221], s[34:35], 0, v[202:203]
	global_load_lds_dwordx4 v[2:3], off
	s_mov_b32 m0, s47
	s_nop 0
	global_load_lds_dwordx4 v[218:219], off
	s_mov_b32 m0, s48
	s_nop 0
	global_load_lds_dwordx4 v[220:221], off
	s_waitcnt vmcnt(8)
	s_waitcnt lgkmcnt(0)
	s_barrier
	s_waitcnt lgkmcnt(0)
	v_mfma_f32_16x16x32_bf16 v[64:67], v[132:135], v[164:167], v[64:67]
	v_mfma_f32_16x16x32_bf16 v[60:63], v[140:143], v[164:167], v[60:63]
	v_mfma_f32_16x16x32_bf16 v[56:59], v[132:135], v[172:175], v[56:59]
	v_mfma_f32_16x16x32_bf16 v[52:55], v[140:143], v[172:175], v[52:55]
	v_mfma_f32_16x16x32_bf16 v[48:51], v[132:135], v[180:183], v[48:51]
	v_mfma_f32_16x16x32_bf16 v[44:47], v[140:143], v[180:183], v[44:47]
	v_mfma_f32_16x16x32_bf16 v[40:43], v[132:135], v[188:191], v[40:43]
	v_mfma_f32_16x16x32_bf16 v[36:39], v[140:143], v[188:191], v[36:39]
	v_mfma_f32_16x16x32_bf16 v[64:67], v[136:139], v[168:171], v[64:67]
	v_mfma_f32_16x16x32_bf16 v[60:63], v[144:147], v[168:171], v[60:63]
	v_mfma_f32_16x16x32_bf16 v[56:59], v[136:139], v[176:179], v[56:59]
	v_mfma_f32_16x16x32_bf16 v[52:55], v[144:147], v[176:179], v[52:55]
	v_mfma_f32_16x16x32_bf16 v[48:51], v[136:139], v[184:187], v[48:51]
	v_mfma_f32_16x16x32_bf16 v[44:47], v[144:147], v[184:187], v[44:47]
	v_mfma_f32_16x16x32_bf16 v[40:43], v[136:139], v[192:195], v[40:43]
	v_mfma_f32_16x16x32_bf16 v[36:39], v[144:147], v[192:195], v[36:39]
	v_mfma_f32_16x16x32_bf16 v[32:35], v[148:151], v[164:167], v[32:35]
	v_mfma_f32_16x16x32_bf16 v[28:31], v[156:159], v[164:167], v[28:31]
	v_mfma_f32_16x16x32_bf16 v[24:27], v[148:151], v[172:175], v[24:27]
	v_mfma_f32_16x16x32_bf16 v[20:23], v[156:159], v[172:175], v[20:23]
	v_mfma_f32_16x16x32_bf16 v[16:19], v[148:151], v[180:183], v[16:19]
	v_mfma_f32_16x16x32_bf16 v[12:15], v[156:159], v[180:183], v[12:15]
	v_mfma_f32_16x16x32_bf16 v[8:11], v[148:151], v[188:191], v[8:11]
	v_mfma_f32_16x16x32_bf16 v[2:5], v[156:159], v[188:191], v[4:7]
	v_mfma_f32_16x16x32_bf16 v[32:35], v[152:155], v[168:171], v[32:35]
	v_mfma_f32_16x16x32_bf16 v[28:31], v[160:163], v[168:171], v[28:31]
	v_mfma_f32_16x16x32_bf16 v[24:27], v[152:155], v[176:179], v[24:27]
	v_mfma_f32_16x16x32_bf16 v[20:23], v[160:163], v[176:179], v[20:23]
	v_mfma_f32_16x16x32_bf16 v[16:19], v[152:155], v[184:187], v[16:19]
	v_mfma_f32_16x16x32_bf16 v[12:15], v[160:163], v[184:187], v[12:15]
	v_mfma_f32_16x16x32_bf16 v[8:11], v[152:155], v[192:195], v[8:11]
	v_mfma_f32_16x16x32_bf16 v[2:5], v[160:163], v[192:195], v[2:5]
	s_barrier
	s_add_i32 s33, 0, 0x18000
	v_add_u32_e32 v1, s33, v226
	s_add_i32 s40, 0, 0x1c000
	ds_read_b128 v[132:135], v1
	ds_read_b128 v[136:139], v1 offset:1024
	ds_read_b128 v[140:143], v1 offset:2048
	ds_read_b128 v[144:147], v1 offset:3072
	v_add_u32_e32 v1, s40, v226
	ds_read_b128 v[148:151], v1
	ds_read_b128 v[152:155], v1 offset:1024
	ds_read_b128 v[156:159], v1 offset:2048
	ds_read_b128 v[160:163], v1 offset:3072
	s_add_u32 s4, s34, 0x1a0000
	s_addc_u32 s5, s35, 0
	s_mov_b32 m0, s49
	v_lshl_add_u64 v[6:7], s[4:5], 0, v[198:199]
	ds_read_b128 v[164:167], v227 offset:32768
	ds_read_b128 v[168:171], v227 offset:33792
	ds_read_b128 v[172:175], v227 offset:34816
	ds_read_b128 v[176:179], v227 offset:35840
	ds_read_b128 v[180:183], v227 offset:36864
	ds_read_b128 v[184:187], v227 offset:37888
	ds_read_b128 v[188:191], v227 offset:38912
	ds_read_b128 v[192:195], v227 offset:39936
	global_load_lds_dwordx4 v[6:7], off
	v_lshl_add_u64 v[6:7], s[4:5], 0, v[202:203]
	s_mov_b32 m0, s50
	s_nop 0
	global_load_lds_dwordx4 v[6:7], off
	s_waitcnt vmcnt(8)
	s_waitcnt lgkmcnt(0)
	s_barrier
	s_waitcnt lgkmcnt(0)
	v_mfma_f32_16x16x32_bf16 v[128:131], v[132:135], v[164:167], v[128:131]
	v_mfma_f32_16x16x32_bf16 v[124:127], v[140:143], v[164:167], v[124:127]
	v_mfma_f32_16x16x32_bf16 v[120:123], v[132:135], v[172:175], v[120:123]
	v_mfma_f32_16x16x32_bf16 v[116:119], v[140:143], v[172:175], v[116:119]
	v_mfma_f32_16x16x32_bf16 v[112:115], v[132:135], v[180:183], v[112:115]
	v_mfma_f32_16x16x32_bf16 v[108:111], v[140:143], v[180:183], v[108:111]
	v_mfma_f32_16x16x32_bf16 v[104:107], v[132:135], v[188:191], v[104:107]
	v_mfma_f32_16x16x32_bf16 v[100:103], v[140:143], v[188:191], v[100:103]
	v_mfma_f32_16x16x32_bf16 v[128:131], v[136:139], v[168:171], v[128:131]
	v_mfma_f32_16x16x32_bf16 v[124:127], v[144:147], v[168:171], v[124:127]
	v_mfma_f32_16x16x32_bf16 v[120:123], v[136:139], v[176:179], v[120:123]
	v_mfma_f32_16x16x32_bf16 v[116:119], v[144:147], v[176:179], v[116:119]
	v_mfma_f32_16x16x32_bf16 v[112:115], v[136:139], v[184:187], v[112:115]
	v_mfma_f32_16x16x32_bf16 v[108:111], v[144:147], v[184:187], v[108:111]
	v_mfma_f32_16x16x32_bf16 v[104:107], v[136:139], v[192:195], v[104:107]
	v_mfma_f32_16x16x32_bf16 v[100:103], v[144:147], v[192:195], v[100:103]
	v_mfma_f32_16x16x32_bf16 v[96:99], v[148:151], v[164:167], v[96:99]
	v_mfma_f32_16x16x32_bf16 v[92:95], v[156:159], v[164:167], v[92:95]
	v_mfma_f32_16x16x32_bf16 v[88:91], v[148:151], v[172:175], v[88:91]
	v_mfma_f32_16x16x32_bf16 v[84:87], v[156:159], v[172:175], v[84:87]
	v_mfma_f32_16x16x32_bf16 v[80:83], v[148:151], v[180:183], v[80:83]
	v_mfma_f32_16x16x32_bf16 v[76:79], v[156:159], v[180:183], v[76:79]
	v_mfma_f32_16x16x32_bf16 v[72:75], v[148:151], v[188:191], v[72:75]
	v_mfma_f32_16x16x32_bf16 v[68:71], v[156:159], v[188:191], v[68:71]
	v_mfma_f32_16x16x32_bf16 v[96:99], v[152:155], v[168:171], v[96:99]
	v_mfma_f32_16x16x32_bf16 v[92:95], v[160:163], v[168:171], v[92:95]
	v_mfma_f32_16x16x32_bf16 v[88:91], v[152:155], v[176:179], v[88:91]
	v_mfma_f32_16x16x32_bf16 v[84:87], v[160:163], v[176:179], v[84:87]
	v_mfma_f32_16x16x32_bf16 v[80:83], v[152:155], v[184:187], v[80:83]
	v_mfma_f32_16x16x32_bf16 v[76:79], v[160:163], v[184:187], v[76:79]
	v_mfma_f32_16x16x32_bf16 v[72:75], v[152:155], v[192:195], v[72:75]
	v_mfma_f32_16x16x32_bf16 v[68:71], v[160:163], v[192:195], v[68:71]
	s_barrier
	s_add_i32 s4, s33, s46
	v_lshl_add_u64 v[6:7], v[214:215], 0, s[18:19]
	s_mov_b32 m0, s4
	ds_read_b128 v[164:167], v227 offset:49152
	ds_read_b128 v[168:171], v227 offset:50176
	ds_read_b128 v[172:175], v227 offset:51200
	ds_read_b128 v[176:179], v227 offset:52224
	ds_read_b128 v[180:183], v227 offset:53248
	ds_read_b128 v[184:187], v227 offset:54272
	ds_read_b128 v[188:191], v227 offset:55296
	ds_read_b128 v[192:195], v227 offset:56320
	global_load_lds_dwordx4 v[6:7], off
	s_add_i32 m0, s4, 0x2000
	s_add_u32 s4, s10, 0x90080
	v_lshl_add_u64 v[6:7], v[216:217], 0, s[18:19]
	s_addc_u32 s5, s11, 0
	s_add_i32 s10, s40, s46
	global_load_lds_dwordx4 v[6:7], off
	v_lshl_add_u64 v[6:7], s[4:5], 0, v[200:201]
	s_mov_b32 m0, s10
	s_nop 0
	global_load_lds_dwordx4 v[6:7], off
	v_lshl_add_u64 v[6:7], s[4:5], 0, v[204:205]
	s_add_i32 m0, s10, 0x2000
	s_nop 0
	global_load_lds_dwordx4 v[6:7], off
	v_lshl_add_u64 v[6:7], v[218:219], 0, s[18:19]
	s_mov_b32 m0, s54
	s_nop 0
	global_load_lds_dwordx4 v[6:7], off
	v_lshl_add_u64 v[6:7], v[220:221], 0, s[18:19]
	s_mov_b32 m0, s55
	s_nop 0
	global_load_lds_dwordx4 v[6:7], off
	s_waitcnt vmcnt(8)
	s_waitcnt lgkmcnt(0)
	s_barrier
	s_waitcnt lgkmcnt(0)
	v_mfma_f32_16x16x32_bf16 v[64:67], v[132:135], v[164:167], v[64:67]
	v_mfma_f32_16x16x32_bf16 v[60:63], v[140:143], v[164:167], v[60:63]
	v_mfma_f32_16x16x32_bf16 v[56:59], v[132:135], v[172:175], v[56:59]
	v_mfma_f32_16x16x32_bf16 v[52:55], v[140:143], v[172:175], v[52:55]
	v_mfma_f32_16x16x32_bf16 v[48:51], v[132:135], v[180:183], v[48:51]
	v_mfma_f32_16x16x32_bf16 v[44:47], v[140:143], v[180:183], v[44:47]
	v_mfma_f32_16x16x32_bf16 v[40:43], v[132:135], v[188:191], v[40:43]
	v_mfma_f32_16x16x32_bf16 v[36:39], v[140:143], v[188:191], v[36:39]
	v_mfma_f32_16x16x32_bf16 v[64:67], v[136:139], v[168:171], v[64:67]
	v_mfma_f32_16x16x32_bf16 v[60:63], v[144:147], v[168:171], v[60:63]
	v_mfma_f32_16x16x32_bf16 v[56:59], v[136:139], v[176:179], v[56:59]
	v_mfma_f32_16x16x32_bf16 v[52:55], v[144:147], v[176:179], v[52:55]
	v_mfma_f32_16x16x32_bf16 v[48:51], v[136:139], v[184:187], v[48:51]
	v_mfma_f32_16x16x32_bf16 v[44:47], v[144:147], v[184:187], v[44:47]
	v_mfma_f32_16x16x32_bf16 v[40:43], v[136:139], v[192:195], v[40:43]
	v_mfma_f32_16x16x32_bf16 v[36:39], v[144:147], v[192:195], v[36:39]
	v_mfma_f32_16x16x32_bf16 v[32:35], v[148:151], v[164:167], v[32:35]
	v_mfma_f32_16x16x32_bf16 v[28:31], v[156:159], v[164:167], v[28:31]
	v_mfma_f32_16x16x32_bf16 v[24:27], v[148:151], v[172:175], v[24:27]
	v_mfma_f32_16x16x32_bf16 v[20:23], v[156:159], v[172:175], v[20:23]
	v_mfma_f32_16x16x32_bf16 v[16:19], v[148:151], v[180:183], v[16:19]
	v_mfma_f32_16x16x32_bf16 v[12:15], v[156:159], v[180:183], v[12:15]
	v_mfma_f32_16x16x32_bf16 v[6:9], v[148:151], v[188:191], v[8:11]
	v_mfma_f32_16x16x32_bf16 v[2:5], v[156:159], v[188:191], v[2:5]
	v_mfma_f32_16x16x32_bf16 v[32:35], v[152:155], v[168:171], v[32:35]
	v_mfma_f32_16x16x32_bf16 v[28:31], v[160:163], v[168:171], v[28:31]
	v_mfma_f32_16x16x32_bf16 v[24:27], v[152:155], v[176:179], v[24:27]
	v_mfma_f32_16x16x32_bf16 v[20:23], v[160:163], v[176:179], v[20:23]
	v_mfma_f32_16x16x32_bf16 v[16:19], v[152:155], v[184:187], v[16:19]
	v_mfma_f32_16x16x32_bf16 v[12:15], v[160:163], v[184:187], v[12:15]
	v_mfma_f32_16x16x32_bf16 v[8:11], v[152:155], v[192:195], v[6:9]
	v_mfma_f32_16x16x32_bf16 v[4:7], v[160:163], v[192:195], v[2:5]
	s_barrier
	s_add_u32 s68, s68, 0x100
	s_addc_u32 s69, s69, 0
	s_add_u32 s8, s8, 0x100
	s_addc_u32 s9, s9, 0
	s_cmp_ge_i32 s70, s67
	s_mov_b32 s4, s70
	s_cbranch_scc0 .LBB0_587
	s_and_b64 vcc, exec, s[20:21]
	s_cbranch_vccz .LBB0_590
	s_barrier

.LBB0_692:
	s_setprio 0
	s_cmp_gt_i32 s77, 8
	s_cselect_b64 s[46:47], -1, 0
	s_and_b64 s[4:5], s[12:13], s[46:47]
	s_andn2_b64 vcc, exec, s[4:5]
	s_cbranch_vccnz .LBB0_738
	s_waitcnt vmcnt(0)
	s_waitcnt vmcnt(0) lgkmcnt(0)
	s_barrier
	s_and_saveexec_b64 s[48:49], s[82:83]
	s_cbranch_execz .LBB0_737
	s_add_i32 s3, 0, 0x20000
	v_mov_b32_e32 v0, s3
	s_waitcnt vmcnt(0) expcnt(0) lgkmcnt(0)
	ds_read_b32 v2, v0
	s_add_i32 s3, 0, 0x20004
	v_mov_b32_e32 v0, s3
	ds_read_b32 v0, v0
	s_waitcnt lgkmcnt(1)
	v_cmp_ne_u32_e32 vcc, 0, v2
	s_cbranch_vccnz .LBB0_708
	s_add_u32 s6, s42, 0x51fda00
	s_addc_u32 s7, s43, 0
	s_add_u32 s10, s42, 0x51fdc00
	s_addc_u32 s11, s43, 0
	s_add_u32 s12, s42, 0x51fdd00
	s_addc_u32 s13, s43, 0
	s_add_u32 s14, s42, 0x51fde00
	s_addc_u32 s15, s43, 0
	s_add_u32 s16, s42, 0x51fdf00
	s_addc_u32 s17, s43, 0
	s_add_u32 s18, s42, 0x51fe000
	s_addc_u32 s19, s43, 0
	s_add_u32 s20, s42, 0x51fe100
	s_addc_u32 s21, s43, 0
	s_add_u32 s22, s42, 0x51fe200
	s_addc_u32 s23, s43, 0
	s_add_u32 s24, s42, 0x51fe300
	s_addc_u32 s25, s43, 0
	s_add_u32 s26, s42, 0x51fe400
	s_addc_u32 s27, s43, 0
	s_add_u32 s28, s42, 0x51fe500
	s_addc_u32 s29, s43, 0
	s_add_u32 s30, s42, 0x51fe600
	s_addc_u32 s31, s43, 0
	s_add_u32 s34, s42, 0x51fe700
	s_addc_u32 s35, s43, 0
	s_add_u32 s36, s42, 0x51fe800
	s_addc_u32 s37, s43, 0
	s_load_dwordx2 s[4:5], s[80:81], 0x4
	s_add_u32 s40, s42, 0x51fe900
	s_addc_u32 s41, s43, 0
	s_add_u32 s44, s42, 0x51fea00
	s_addc_u32 s45, s43, 0
	s_add_u32 s50, s42, 0x51feb00
	s_waitcnt lgkmcnt(0)
	s_mul_i32 s3, s4, s38
	s_addc_u32 s51, s43, 0
	s_mul_i32 s3, s3, s5
	s_mov_b32 s4, 1
	s_mov_b64 s[8:9], 0
	v_mov_b64_e32 v[0:1], s[10:11]
	v_mov_b64_e32 v[2:3], s[12:13]
	v_mov_b64_e32 v[4:5], s[14:15]
	v_mov_b64_e32 v[6:7], s[16:17]
	v_mov_b64_e32 v[8:9], s[18:19]
	v_mov_b64_e32 v[10:11], s[20:21]
	v_mov_b64_e32 v[12:13], s[22:23]
	v_mov_b64_e32 v[14:15], s[24:25]
	v_mov_b64_e32 v[16:17], s[26:27]
	v_mov_b64_e32 v[18:19], s[28:29]
	v_mov_b64_e32 v[20:21], s[30:31]
	v_mov_b64_e32 v[22:23], s[34:35]
	v_mov_b64_e32 v[24:25], s[36:37]
	v_mov_b64_e32 v[26:27], s[40:41]
	v_mov_b64_e32 v[28:29], s[44:45]
	v_mov_b64_e32 v[30:31], s[50:51]
	s_branch .LBB0_698

.LBB0_738:
	s_cmp_lt_i32 s76, 9
	s_cselect_b64 s[10:11], -1, 0
	s_and_b64 s[4:5], s[10:11], s[46:47]
	s_andn2_b64 vcc, exec, s[4:5]
	s_cbranch_vccnz .LBB0_761
	s_cmpk_gt_i32 s2, 0x3ff
	s_mov_b64 s[6:7], s[0:1]
	v_readfirstlane_b32 s9, v196
	s_waitcnt vmcnt(0) lgkmcnt(0)
	s_barrier
	s_cbranch_scc1 .LBB0_761
	s_lshr_b32 s99, s9, 8
	s_cmp_eq_u32 s99, 1
	s_cbranch_scc0 .Lprio_p8
	s_setprio 1
.Lprio_p8:
	v_lshrrev_b32_e32 v2, 3, v196
	s_movk_i32 s3, 0x70
	v_lshlrev_b32_e32 v0, 4, v196
	v_and_or_b32 v3, v2, s3, v222
	v_mul_u32_u24_e32 v8, 0x3400, v3
	v_add_u32_e32 v3, 0x2000, v0
	v_lshrrev_b32_e32 v3, 7, v3
	s_movk_i32 s3, 0xf0
	v_and_or_b32 v4, v3, s3, v222
	v_lshrrev_b32_e32 v1, 2, v196
	v_mul_u32_u24_e32 v10, 0x3400, v4
	v_and_b32_e32 v4, 32, v196
	s_load_dwordx4 s[12:15], s[6:7], 0xd8
	v_bitop3_b32 v9, v0, v4, 48 bitop3:0x6c
	v_lshlrev_b32_e32 v4, 1, v1
	v_lshrrev_b32_e32 v5, 5, v196
	v_and_b32_e32 v4, 24, v4
	v_and_b32_e32 v5, 4, v5
	v_and_b32_e32 v1, 3, v1
	v_or3_b32 v1, v5, v1, v4
	s_movk_i32 s3, 0x60
	v_and_or_b32 v2, v2, s3, v1
	s_movk_i32 s3, 0xe0
	v_and_or_b32 v1, v3, s3, v1
	s_waitcnt lgkmcnt(0)
	s_add_u32 s3, s14, 0x5200e00
	s_addc_u32 s34, s15, 0
	s_add_u32 s35, s14, 0x1400000
	s_addc_u32 s36, s15, 0
	s_ashr_i32 s39, s2, 31
	s_lshr_b32 s8, s39, 29
	s_add_i32 s8, s2, s8
	s_ashr_i32 s16, s8, 3
	s_and_b32 s8, s8, -8
	s_lshr_b32 s4, s9, 6
	s_sub_i32 s8, s2, s8
	s_lshr_b32 s5, s9, 8
	s_lshl_b32 s37, s4, 10
	s_lshl_b32 s18, s8, 7
	s_mul_i32 s17, s8, 0x81
	s_cmp_lt_i32 s8, 0
	s_cselect_b32 s8, s17, s18
	s_add_i32 s8, s8, s16
	s_ashr_i32 s16, s8, 31
	s_lshr_b32 s16, s16, 27
	s_add_i32 s16, s8, s16
	s_ashr_i32 s17, s16, 5
	s_andn2_b32 s16, s16, 31
	s_sub_i32 s16, s8, s16
	s_bfe_i32 s8, s16, 0x80000
	s_bfe_u32 s8, s8, 0x3000c
	s_add_i32 s18, s16, s8
	s_bfe_i32 s8, s18, 0x80000
	s_sext_i32_i16 s8, s8
	s_and_b32 s18, s18, 0xf8
	s_lshr_b32 s8, s8, 3
	s_sub_i32 s16, s16, s18
	s_lshl_b32 s17, s17, 3
	s_sext_i32_i8 s16, s16
	s_bfe_i64 s[18:19], s[8:9], 0x100000
	s_add_i32 s16, s17, s16
	s_lshl_b64 s[18:19], s[18:19], 19
	v_and_b32_e32 v11, 64, v196
	s_add_u32 s28, s35, s18
	v_or_b32_e32 v0, v9, v11
	s_addc_u32 s29, s36, s19
	s_add_i32 s46, s37, 0
	v_lshl_or_b32 v146, v2, 11, v0
	s_add_i32 m0, s46, 0x10000
	v_lshl_or_b32 v150, v1, 11, v0
	global_load_lds_dwordx4 v146, s[28:29]
	s_add_i32 m0, s46, 0x12000
	s_add_u32 s18, s28, 0x40000
	global_load_lds_dwordx4 v150, s[28:29]
	s_addc_u32 s19, s29, 0
	s_add_i32 m0, s46, 0x14000
	s_mul_i32 s20, s16, 0x340000
	global_load_lds_dwordx4 v146, s[18:19]
	s_add_i32 m0, s46, 0x16000
	s_mul_hi_i32 s17, s16, 0x340000
	s_add_u32 s30, s3, s20
	s_addc_u32 s31, s34, s17
	s_add_i32 s47, s46, 0x2000
	v_or_b32_e32 v144, v0, v8
	global_load_lds_dwordx4 v150, s[18:19]
	s_mov_b32 m0, s46
	s_add_u32 s18, s30, 0x1a0000
	v_or_b32_e32 v148, v10, v0
	global_load_lds_dwordx4 v144, s[30:31]
	s_mov_b32 m0, s47
	s_addc_u32 s19, s31, 0
	s_add_i32 s48, s46, 0x4000
	global_load_lds_dwordx4 v148, s[30:31]
	s_mov_b32 m0, s48
	s_add_i32 s49, s46, 0x6000
	global_load_lds_dwordx4 v144, s[18:19]
	s_mov_b32 m0, s49
	s_load_dwordx2 s[6:7], s[6:7], 0x0
	global_load_lds_dwordx4 v148, s[18:19]
	v_mov_b32_e32 v147, 0
	v_mov_b32_e32 v151, v147
	v_mov_b32_e32 v145, v147
	v_mov_b32_e32 v149, v147
	s_cmp_eq_u32 s5, 1
	s_mov_b32 s17, 0
	v_lshl_add_u64 v[6:7], s[28:29], 0, v[146:147]
	v_lshl_add_u64 v[4:5], s[28:29], 0, v[150:151]
	v_lshl_add_u64 v[0:1], s[30:31], 0, v[144:145]
	s_cselect_b64 s[18:19], -1, 0
	s_cmp_lg_u32 s5, 1
	v_lshl_add_u64 v[2:3], s[30:31], 0, v[148:149]
	s_cbranch_scc1 .LBB0_742
	s_barrier

.LBB0_754:
	ds_read_b128 v[128:131], v169
	ds_read_b128 v[132:135], v169 offset:1024
	ds_read_b128 v[136:139], v169 offset:2048
	ds_read_b128 v[140:143], v169 offset:3072
	ds_read_b128 v[160:163], v170
	ds_read_b128 v[172:175], v170 offset:1024
	ds_read_b128 v[176:179], v170 offset:2048
	ds_read_b128 v[180:183], v170 offset:3072
	s_add_u32 s4, s8, 0xffe60080
	s_addc_u32 s5, s9, -1
	s_cmp_eq_u32 s67, 12
	s_cselect_b32 s31, s25, s5
	s_cselect_b32 s30, s24, s4
	s_cselect_b32 s29, s23, s66
	s_cselect_b32 s28, s64, s65
	v_lshl_add_u64 v[164:165], s[8:9], 0, v[154:155]
	s_add_i32 m0, s46, 0xc000
	ds_read_b128 v[184:187], v171
	ds_read_b128 v[188:191], v171 offset:1024
	ds_read_b128 v[192:195], v171 offset:2048
	ds_read_b128 v[198:201], v171 offset:3072
	ds_read_b128 v[202:205], v171 offset:4096
	ds_read_b128 v[206:209], v171 offset:5120
	ds_read_b128 v[210:213], v171 offset:6144
	ds_read_b128 v[214:217], v171 offset:7168
	global_load_lds_dwordx4 v[164:165], off
	v_lshl_add_u64 v[164:165], s[8:9], 0, v[152:153]
	s_add_i32 m0, s46, 0xe000
	s_nop 0
	global_load_lds_dwordx4 v[164:165], off
	s_waitcnt vmcnt(8)
	s_waitcnt lgkmcnt(0)
	s_barrier
	s_waitcnt lgkmcnt(0)
	v_mfma_f32_16x16x32_bf16 v[124:127], v[128:131], v[184:187], v[124:127]
	v_mfma_f32_16x16x32_bf16 v[120:123], v[136:139], v[184:187], v[120:123]
	v_mfma_f32_16x16x32_bf16 v[116:119], v[128:131], v[192:195], v[116:119]
	v_mfma_f32_16x16x32_bf16 v[112:115], v[136:139], v[192:195], v[112:115]
	v_mfma_f32_16x16x32_bf16 v[96:99], v[128:131], v[202:205], v[96:99]
	v_mfma_f32_16x16x32_bf16 v[88:91], v[136:139], v[202:205], v[88:91]
	v_mfma_f32_16x16x32_bf16 v[80:83], v[128:131], v[210:213], v[80:83]
	v_mfma_f32_16x16x32_bf16 v[72:75], v[136:139], v[210:213], v[72:75]
	v_mfma_f32_16x16x32_bf16 v[124:127], v[132:135], v[188:191], v[124:127]
	v_mfma_f32_16x16x32_bf16 v[120:123], v[140:143], v[188:191], v[120:123]
	v_mfma_f32_16x16x32_bf16 v[116:119], v[132:135], v[198:201], v[116:119]
	v_mfma_f32_16x16x32_bf16 v[112:115], v[140:143], v[198:201], v[112:115]
	v_mfma_f32_16x16x32_bf16 v[96:99], v[132:135], v[206:209], v[96:99]
	v_mfma_f32_16x16x32_bf16 v[88:91], v[140:143], v[206:209], v[88:91]
	v_mfma_f32_16x16x32_bf16 v[80:83], v[132:135], v[214:217], v[80:83]
	v_mfma_f32_16x16x32_bf16 v[72:75], v[140:143], v[214:217], v[72:75]
	v_mfma_f32_16x16x32_bf16 v[108:111], v[160:163], v[184:187], v[108:111]
	v_mfma_f32_16x16x32_bf16 v[104:107], v[176:179], v[184:187], v[104:107]
	v_mfma_f32_16x16x32_bf16 v[100:103], v[160:163], v[192:195], v[100:103]
	v_mfma_f32_16x16x32_bf16 v[92:95], v[176:179], v[192:195], v[92:95]
	v_mfma_f32_16x16x32_bf16 v[84:87], v[160:163], v[202:205], v[84:87]
	v_mfma_f32_16x16x32_bf16 v[76:79], v[176:179], v[202:205], v[76:79]
	v_mfma_f32_16x16x32_bf16 v[68:71], v[160:163], v[210:213], v[68:71]
	v_mfma_f32_16x16x32_bf16 v[64:67], v[176:179], v[210:213], v[64:67]
	v_mfma_f32_16x16x32_bf16 v[108:111], v[172:175], v[188:191], v[108:111]
	v_mfma_f32_16x16x32_bf16 v[104:107], v[180:183], v[188:191], v[104:107]
	v_mfma_f32_16x16x32_bf16 v[100:103], v[172:175], v[198:201], v[100:103]
	v_mfma_f32_16x16x32_bf16 v[92:95], v[180:183], v[198:201], v[92:95]
	v_mfma_f32_16x16x32_bf16 v[84:87], v[172:175], v[206:209], v[84:87]
	v_mfma_f32_16x16x32_bf16 v[76:79], v[180:183], v[206:209], v[76:79]
	v_mfma_f32_16x16x32_bf16 v[68:71], v[172:175], v[214:217], v[68:71]
	v_mfma_f32_16x16x32_bf16 v[64:67], v[180:183], v[214:217], v[64:67]
	s_barrier
	s_add_i32 s4, s59, s37
	v_lshl_add_u64 v[164:165], s[28:29], 0, v[146:147]
	s_mov_b32 m0, s4
	ds_read_b128 v[184:187], v171 offset:16384
	ds_read_b128 v[188:191], v171 offset:17408
	ds_read_b128 v[192:195], v171 offset:18432
	ds_read_b128 v[198:201], v171 offset:19456
	ds_read_b128 v[202:205], v171 offset:20480
	ds_read_b128 v[206:209], v171 offset:21504
	ds_read_b128 v[210:213], v171 offset:22528
	ds_read_b128 v[214:217], v171 offset:23552
	global_load_lds_dwordx4 v[164:165], off
	s_add_i32 m0, s4, 0x2000
	s_add_u32 s4, s28, 0x40000
	v_lshl_add_u64 v[218:219], s[28:29], 0, v[150:151]
	s_addc_u32 s5, s29, 0
	s_add_i32 s33, s60, s37
	global_load_lds_dwordx4 v[218:219], off
	v_lshl_add_u64 v[220:221], s[4:5], 0, v[146:147]
	s_mov_b32 m0, s33
	v_lshl_add_u64 v[224:225], s[30:31], 0, v[148:149]
	global_load_lds_dwordx4 v[220:221], off
	v_lshl_add_u64 v[220:221], s[4:5], 0, v[150:151]
	s_add_i32 m0, s33, 0x2000
	s_nop 0
	global_load_lds_dwordx4 v[220:221], off
	v_lshl_add_u64 v[220:221], s[30:31], 0, v[144:145]
	s_mov_b32 m0, s46
	s_nop 0
	global_load_lds_dwordx4 v[220:221], off
	s_mov_b32 m0, s47
	s_nop 0
	global_load_lds_dwordx4 v[224:225], off
	s_waitcnt vmcnt(8)
	s_waitcnt lgkmcnt(0)
	s_barrier
	s_waitcnt lgkmcnt(0)
	v_mfma_f32_16x16x32_bf16 v[60:63], v[128:131], v[184:187], v[60:63]
	v_mfma_f32_16x16x32_bf16 v[56:59], v[136:139], v[184:187], v[56:59]
	v_mfma_f32_16x16x32_bf16 v[48:51], v[128:131], v[192:195], v[48:51]
	v_mfma_f32_16x16x32_bf16 v[40:43], v[136:139], v[192:195], v[40:43]
	v_mfma_f32_16x16x32_bf16 v[32:35], v[128:131], v[202:205], v[32:35]
	v_mfma_f32_16x16x32_bf16 v[24:27], v[136:139], v[202:205], v[24:27]
	v_mfma_f32_16x16x32_bf16 v[16:19], v[128:131], v[210:213], v[16:19]
	v_mfma_f32_16x16x32_bf16 v[8:11], v[136:139], v[210:213], v[8:11]
	v_mfma_f32_16x16x32_bf16 v[60:63], v[132:135], v[188:191], v[60:63]
	v_mfma_f32_16x16x32_bf16 v[56:59], v[140:143], v[188:191], v[56:59]
	v_mfma_f32_16x16x32_bf16 v[48:51], v[132:135], v[198:201], v[48:51]
	v_mfma_f32_16x16x32_bf16 v[40:43], v[140:143], v[198:201], v[40:43]
	v_mfma_f32_16x16x32_bf16 v[32:35], v[132:135], v[206:209], v[32:35]
	v_mfma_f32_16x16x32_bf16 v[24:27], v[140:143], v[206:209], v[24:27]
	v_mfma_f32_16x16x32_bf16 v[16:19], v[132:135], v[214:217], v[16:19]
	v_mfma_f32_16x16x32_bf16 v[8:11], v[140:143], v[214:217], v[8:11]
	v_mfma_f32_16x16x32_bf16 v[52:55], v[160:163], v[184:187], v[52:55]
	v_mfma_f32_16x16x32_bf16 v[44:47], v[176:179], v[184:187], v[44:47]
	v_mfma_f32_16x16x32_bf16 v[36:39], v[160:163], v[192:195], v[36:39]
	v_mfma_f32_16x16x32_bf16 v[28:31], v[176:179], v[192:195], v[28:31]
	v_mfma_f32_16x16x32_bf16 v[20:23], v[160:163], v[202:205], v[20:23]
	v_mfma_f32_16x16x32_bf16 v[12:15], v[176:179], v[202:205], v[12:15]
	v_mfma_f32_16x16x32_bf16 v[4:7], v[160:163], v[210:213], v[4:7]
	v_mfma_f32_16x16x32_bf16 v[0:3], v[176:179], v[210:213], v[0:3]
	v_mfma_f32_16x16x32_bf16 v[52:55], v[172:175], v[188:191], v[52:55]
	v_mfma_f32_16x16x32_bf16 v[44:47], v[180:183], v[188:191], v[44:47]
	v_mfma_f32_16x16x32_bf16 v[36:39], v[172:175], v[198:201], v[36:39]
	v_mfma_f32_16x16x32_bf16 v[28:31], v[180:183], v[198:201], v[28:31]
	v_mfma_f32_16x16x32_bf16 v[20:23], v[172:175], v[206:209], v[20:23]
	v_mfma_f32_16x16x32_bf16 v[12:15], v[180:183], v[206:209], v[12:15]
	v_mfma_f32_16x16x32_bf16 v[4:7], v[172:175], v[214:217], v[4:7]
	v_mfma_f32_16x16x32_bf16 v[0:3], v[180:183], v[214:217], v[0:3]
	s_barrier
	s_add_i32 s33, 0, 0x18000
	s_add_i32 s40, 0, 0x1c000
	v_add_u32_e32 v140, s33, v168
	v_add_u32_e32 v180, s40, v168
	ds_read_b128 v[128:131], v140
	ds_read_b128 v[132:135], v140 offset:1024
	ds_read_b128 v[136:139], v140 offset:2048
	ds_read_b128 v[140:143], v140 offset:3072
	ds_read_b128 v[160:163], v180
	ds_read_b128 v[172:175], v180 offset:1024
	ds_read_b128 v[176:179], v180 offset:2048
	ds_read_b128 v[180:183], v180 offset:3072
	s_add_u32 s4, s30, 0x1a0000
	s_addc_u32 s5, s31, 0
	s_mov_b32 m0, s48
	v_lshl_add_u64 v[226:227], s[4:5], 0, v[144:145]
	ds_read_b128 v[184:187], v171 offset:32768
	ds_read_b128 v[188:191], v171 offset:33792
	ds_read_b128 v[192:195], v171 offset:34816
	ds_read_b128 v[198:201], v171 offset:35840
	ds_read_b128 v[202:205], v171 offset:36864
	ds_read_b128 v[206:209], v171 offset:37888
	ds_read_b128 v[210:213], v171 offset:38912
	ds_read_b128 v[214:217], v171 offset:39936
	global_load_lds_dwordx4 v[226:227], off
	v_lshl_add_u64 v[226:227], s[4:5], 0, v[148:149]
	s_mov_b32 m0, s49
	s_nop 0
	global_load_lds_dwordx4 v[226:227], off
	s_waitcnt vmcnt(8)
	s_waitcnt lgkmcnt(0)
	s_barrier
	s_waitcnt lgkmcnt(0)
	v_mfma_f32_16x16x32_bf16 v[124:127], v[128:131], v[184:187], v[124:127]
	v_mfma_f32_16x16x32_bf16 v[120:123], v[136:139], v[184:187], v[120:123]
	v_mfma_f32_16x16x32_bf16 v[116:119], v[128:131], v[192:195], v[116:119]
	v_mfma_f32_16x16x32_bf16 v[112:115], v[136:139], v[192:195], v[112:115]
	v_mfma_f32_16x16x32_bf16 v[96:99], v[128:131], v[202:205], v[96:99]
	v_mfma_f32_16x16x32_bf16 v[88:91], v[136:139], v[202:205], v[88:91]
	v_mfma_f32_16x16x32_bf16 v[80:83], v[128:131], v[210:213], v[80:83]
	v_mfma_f32_16x16x32_bf16 v[72:75], v[136:139], v[210:213], v[72:75]
	v_mfma_f32_16x16x32_bf16 v[124:127], v[132:135], v[188:191], v[124:127]
	v_mfma_f32_16x16x32_bf16 v[120:123], v[140:143], v[188:191], v[120:123]
	v_mfma_f32_16x16x32_bf16 v[116:119], v[132:135], v[198:201], v[116:119]
	v_mfma_f32_16x16x32_bf16 v[112:115], v[140:143], v[198:201], v[112:115]
	v_mfma_f32_16x16x32_bf16 v[96:99], v[132:135], v[206:209], v[96:99]
	v_mfma_f32_16x16x32_bf16 v[88:91], v[140:143], v[206:209], v[88:91]
	v_mfma_f32_16x16x32_bf16 v[80:83], v[132:135], v[214:217], v[80:83]
	v_mfma_f32_16x16x32_bf16 v[72:75], v[140:143], v[214:217], v[72:75]
	v_mfma_f32_16x16x32_bf16 v[108:111], v[160:163], v[184:187], v[108:111]
	v_mfma_f32_16x16x32_bf16 v[104:107], v[176:179], v[184:187], v[104:107]
	v_mfma_f32_16x16x32_bf16 v[100:103], v[160:163], v[192:195], v[100:103]
	v_mfma_f32_16x16x32_bf16 v[92:95], v[176:179], v[192:195], v[92:95]
	v_mfma_f32_16x16x32_bf16 v[84:87], v[160:163], v[202:205], v[84:87]
	v_mfma_f32_16x16x32_bf16 v[76:79], v[176:179], v[202:205], v[76:79]
	v_mfma_f32_16x16x32_bf16 v[68:71], v[160:163], v[210:213], v[68:71]
	v_mfma_f32_16x16x32_bf16 v[64:67], v[176:179], v[210:213], v[64:67]
	v_mfma_f32_16x16x32_bf16 v[108:111], v[172:175], v[188:191], v[108:111]
	v_mfma_f32_16x16x32_bf16 v[104:107], v[180:183], v[188:191], v[104:107]
	v_mfma_f32_16x16x32_bf16 v[100:103], v[172:175], v[198:201], v[100:103]
	v_mfma_f32_16x16x32_bf16 v[92:95], v[180:183], v[198:201], v[92:95]
	v_mfma_f32_16x16x32_bf16 v[84:87], v[172:175], v[206:209], v[84:87]
	v_mfma_f32_16x16x32_bf16 v[76:79], v[180:183], v[206:209], v[76:79]
	v_mfma_f32_16x16x32_bf16 v[68:71], v[172:175], v[214:217], v[68:71]
	v_mfma_f32_16x16x32_bf16 v[64:67], v[180:183], v[214:217], v[64:67]
	s_barrier
	s_add_i32 s4, s33, s37
	v_lshl_add_u64 v[164:165], v[164:165], 0, s[14:15]
	s_mov_b32 m0, s4
	ds_read_b128 v[184:187], v171 offset:49152
	ds_read_b128 v[188:191], v171 offset:50176
	ds_read_b128 v[192:195], v171 offset:51200
	ds_read_b128 v[198:201], v171 offset:52224
	ds_read_b128 v[202:205], v171 offset:53248
	ds_read_b128 v[206:209], v171 offset:54272
	ds_read_b128 v[210:213], v171 offset:55296
	ds_read_b128 v[214:217], v171 offset:56320
	global_load_lds_dwordx4 v[164:165], off
	s_add_i32 m0, s4, 0x2000
	s_add_u32 s4, s28, 0x40080
	v_lshl_add_u64 v[164:165], v[218:219], 0, s[14:15]
	s_addc_u32 s5, s29, 0
	s_add_i32 s28, s40, s37
	global_load_lds_dwordx4 v[164:165], off
	v_lshl_add_u64 v[164:165], s[4:5], 0, v[146:147]
	s_mov_b32 m0, s28
	s_nop 0
	global_load_lds_dwordx4 v[164:165], off
	v_lshl_add_u64 v[164:165], s[4:5], 0, v[150:151]
	s_add_i32 m0, s28, 0x2000
	s_nop 0
	global_load_lds_dwordx4 v[164:165], off
	v_lshl_add_u64 v[164:165], v[220:221], 0, s[14:15]
	s_mov_b32 m0, s55
	s_nop 0
	global_load_lds_dwordx4 v[164:165], off
	v_lshl_add_u64 v[164:165], v[224:225], 0, s[14:15]
	s_mov_b32 m0, s56
	s_nop 0
	global_load_lds_dwordx4 v[164:165], off
	s_waitcnt vmcnt(8)
	s_waitcnt lgkmcnt(0)
	s_barrier
	s_waitcnt lgkmcnt(0)
	v_mfma_f32_16x16x32_bf16 v[60:63], v[128:131], v[184:187], v[60:63]
	v_mfma_f32_16x16x32_bf16 v[56:59], v[136:139], v[184:187], v[56:59]
	v_mfma_f32_16x16x32_bf16 v[48:51], v[128:131], v[192:195], v[48:51]
	v_mfma_f32_16x16x32_bf16 v[40:43], v[136:139], v[192:195], v[40:43]
	v_mfma_f32_16x16x32_bf16 v[32:35], v[128:131], v[202:205], v[32:35]
	v_mfma_f32_16x16x32_bf16 v[24:27], v[136:139], v[202:205], v[24:27]
	v_mfma_f32_16x16x32_bf16 v[16:19], v[128:131], v[210:213], v[16:19]
	v_mfma_f32_16x16x32_bf16 v[8:11], v[136:139], v[210:213], v[8:11]
	v_mfma_f32_16x16x32_bf16 v[60:63], v[132:135], v[188:191], v[60:63]
	v_mfma_f32_16x16x32_bf16 v[56:59], v[140:143], v[188:191], v[56:59]
	v_mfma_f32_16x16x32_bf16 v[48:51], v[132:135], v[198:201], v[48:51]
	v_mfma_f32_16x16x32_bf16 v[40:43], v[140:143], v[198:201], v[40:43]
	v_mfma_f32_16x16x32_bf16 v[32:35], v[132:135], v[206:209], v[32:35]
	v_mfma_f32_16x16x32_bf16 v[24:27], v[140:143], v[206:209], v[24:27]
	v_mfma_f32_16x16x32_bf16 v[16:19], v[132:135], v[214:217], v[16:19]
	v_mfma_f32_16x16x32_bf16 v[8:11], v[140:143], v[214:217], v[8:11]
	v_mfma_f32_16x16x32_bf16 v[52:55], v[160:163], v[184:187], v[52:55]
	v_mfma_f32_16x16x32_bf16 v[44:47], v[176:179], v[184:187], v[44:47]
	v_mfma_f32_16x16x32_bf16 v[36:39], v[160:163], v[192:195], v[36:39]
	v_mfma_f32_16x16x32_bf16 v[28:31], v[176:179], v[192:195], v[28:31]
	v_mfma_f32_16x16x32_bf16 v[20:23], v[160:163], v[202:205], v[20:23]
	v_mfma_f32_16x16x32_bf16 v[12:15], v[176:179], v[202:205], v[12:15]
	v_mfma_f32_16x16x32_bf16 v[4:7], v[160:163], v[210:213], v[4:7]
	v_mfma_f32_16x16x32_bf16 v[0:3], v[176:179], v[210:213], v[0:3]
	v_mfma_f32_16x16x32_bf16 v[52:55], v[172:175], v[188:191], v[52:55]
	v_mfma_f32_16x16x32_bf16 v[44:47], v[180:183], v[188:191], v[44:47]
	v_mfma_f32_16x16x32_bf16 v[36:39], v[172:175], v[198:201], v[36:39]
	v_mfma_f32_16x16x32_bf16 v[28:31], v[180:183], v[198:201], v[28:31]
	v_mfma_f32_16x16x32_bf16 v[20:23], v[172:175], v[206:209], v[20:23]
	v_mfma_f32_16x16x32_bf16 v[12:15], v[180:183], v[206:209], v[12:15]
	v_mfma_f32_16x16x32_bf16 v[4:7], v[172:175], v[214:217], v[4:7]
	v_mfma_f32_16x16x32_bf16 v[0:3], v[180:183], v[214:217], v[0:3]
	s_barrier
	s_add_i32 s67, s67, 2
	s_add_u32 s65, s65, 0x100
	s_addc_u32 s66, s66, 0
	s_add_u32 s8, s8, 0x100
	s_addc_u32 s9, s9, 0
	s_cmp_gt_u32 s67, 13
	s_cbranch_scc0 .LBB0_754
	s_and_b64 vcc, exec, s[20:21]
	s_cbranch_vccz .LBB0_757
	s_barrier

.LBB0_761:
	s_setprio 0
	s_cmp_gt_i32 s77, 9
	s_cselect_b64 s[46:47], -1, 0
	s_and_b64 s[4:5], s[10:11], s[46:47]
	s_andn2_b64 vcc, exec, s[4:5]
	s_cbranch_vccnz .LBB0_807
	s_waitcnt vmcnt(0)
	s_waitcnt vmcnt(0) lgkmcnt(0)
	s_barrier
	s_and_saveexec_b64 s[48:49], s[82:83]
	s_cbranch_execz .LBB0_806
	s_add_i32 s3, 0, 0x20000
	v_mov_b32_e32 v0, s3
	s_waitcnt vmcnt(0) expcnt(0) lgkmcnt(0)
	ds_read_b32 v2, v0
	s_add_i32 s3, 0, 0x20004
	v_mov_b32_e32 v0, s3
	ds_read_b32 v0, v0
	s_waitcnt lgkmcnt(1)
	v_cmp_ne_u32_e32 vcc, 0, v2
	s_cbranch_vccnz .LBB0_777
	s_add_u32 s6, s42, 0x51fda00
	s_addc_u32 s7, s43, 0
	s_add_u32 s10, s42, 0x51fdc00
	s_addc_u32 s11, s43, 0
	s_add_u32 s12, s42, 0x51fdd00
	s_addc_u32 s13, s43, 0
	s_add_u32 s14, s42, 0x51fde00
	s_addc_u32 s15, s43, 0
	s_add_u32 s16, s42, 0x51fdf00
	s_addc_u32 s17, s43, 0
	s_add_u32 s18, s42, 0x51fe000
	s_addc_u32 s19, s43, 0
	s_add_u32 s20, s42, 0x51fe100
	s_addc_u32 s21, s43, 0
	s_add_u32 s22, s42, 0x51fe200
	s_addc_u32 s23, s43, 0
	s_add_u32 s24, s42, 0x51fe300
	s_addc_u32 s25, s43, 0
	s_add_u32 s26, s42, 0x51fe400
	s_addc_u32 s27, s43, 0
	s_add_u32 s28, s42, 0x51fe500
	s_addc_u32 s29, s43, 0
	s_add_u32 s30, s42, 0x51fe600
	s_addc_u32 s31, s43, 0
	s_add_u32 s34, s42, 0x51fe700
	s_addc_u32 s35, s43, 0
	s_add_u32 s36, s42, 0x51fe800
	s_addc_u32 s37, s43, 0
	s_load_dwordx2 s[4:5], s[80:81], 0x4
	s_add_u32 s40, s42, 0x51fe900
	s_addc_u32 s41, s43, 0
	s_add_u32 s44, s42, 0x51fea00
	s_addc_u32 s45, s43, 0
	s_add_u32 s50, s42, 0x51feb00
	s_waitcnt lgkmcnt(0)
	s_mul_i32 s3, s4, s38
	s_addc_u32 s51, s43, 0
	s_mul_i32 s3, s3, s5
	s_mov_b32 s4, 1
	s_mov_b64 s[8:9], 0
	v_mov_b64_e32 v[0:1], s[10:11]
	v_mov_b64_e32 v[2:3], s[12:13]
	v_mov_b64_e32 v[4:5], s[14:15]
	v_mov_b64_e32 v[6:7], s[16:17]
	v_mov_b64_e32 v[8:9], s[18:19]
	v_mov_b64_e32 v[10:11], s[20:21]
	v_mov_b64_e32 v[12:13], s[22:23]
	v_mov_b64_e32 v[14:15], s[24:25]
	v_mov_b64_e32 v[16:17], s[26:27]
	v_mov_b64_e32 v[18:19], s[28:29]
	v_mov_b64_e32 v[20:21], s[30:31]
	v_mov_b64_e32 v[22:23], s[34:35]
	v_mov_b64_e32 v[24:25], s[36:37]
	v_mov_b64_e32 v[26:27], s[40:41]
	v_mov_b64_e32 v[28:29], s[44:45]
	v_mov_b64_e32 v[30:31], s[50:51]
	s_branch .LBB0_767

.LBB0_865:
	s_cmp_lt_i32 s76, 11
	s_cselect_b64 s[8:9], -1, 0
	s_and_b64 s[4:5], s[8:9], s[46:47]
	s_andn2_b64 vcc, exec, s[4:5]
	s_cbranch_vccnz .LBB0_882
	s_cmpk_gt_i32 s2, 0x15ff
	s_mov_b64 s[6:7], s[0:1]
	v_readfirstlane_b32 s16, v196
	s_waitcnt vmcnt(0) lgkmcnt(0)
	s_barrier
	s_cbranch_scc1 .LBB0_882
	s_lshr_b32 s99, s16, 8
	s_cmp_eq_u32 s99, 1
	s_cbranch_scc0 .Lprio_p10
	s_setprio 1
.Lprio_p10:
	v_lshrrev_b32_e32 v2, 1, v196
	v_lshrrev_b32_e32 v3, 5, v196
	v_and_b32_e32 v2, 24, v2
	v_and_b32_e32 v3, 4, v3
	s_load_dwordx2 s[10:11], s[6:7], 0xe0
	v_lshlrev_b32_e32 v0, 4, v196
	v_and_b32_e32 v1, 32, v196
	v_or3_b32 v2, v3, v223, v2
	v_lshrrev_b32_e32 v3, 3, v196
	s_movk_i32 s3, 0x70
	v_bitop3_b32 v8, v0, v1, 48 bitop3:0x6c
	v_and_b32_e32 v9, 64, v196
	v_and_or_b32 v4, v3, s3, v222
	s_movk_i32 s3, 0x60
	v_add_u32_e32 v10, 0x2000, v0
	v_or_b32_e32 v1, v8, v9
	v_and_or_b32 v3, v3, s3, v2
	v_lshrrev_b32_e32 v0, 7, v10
	s_movk_i32 s3, 0xf0
	v_lshl_or_b32 v130, v3, 11, v1
	v_and_or_b32 v3, v0, s3, v222
	s_movk_i32 s3, 0xe0
	v_and_or_b32 v0, v0, s3, v2
	s_waitcnt lgkmcnt(0)
	s_add_u32 s3, s10, 0x5200e00
	s_addc_u32 s36, s11, 0
	s_add_u32 s37, s10, 0x1600000
	s_addc_u32 s39, s11, 0
	s_ashr_i32 s47, s2, 31
	s_lshr_b32 s6, s47, 29
	s_add_i32 s6, s2, s6
	s_lshr_b32 s4, s16, 6
	s_ashr_i32 s7, s6, 3
	s_and_b32 s6, s6, -8
	s_lshr_b32 s5, s16, 8
	s_lshl_b32 s46, s4, 10
	s_sub_i32 s6, s2, s6
	s_cmp_lt_i32 s6, 0
	s_movk_i32 s48, 0x2c1
	s_cselect_b32 s12, s48, 0x2c0
	s_mul_i32 s6, s6, s12
	s_add_i32 s6, s6, s7
	s_mul_hi_i32 s7, s6, 0x2e8ba2e9
	s_lshr_b32 s12, s7, 31
	s_ashr_i32 s7, s7, 5
	s_add_i32 s7, s7, s12
	s_lshl_b32 s12, s7, 3
	s_mulk_i32 s7, 0xb0
	s_sub_i32 s7, s6, s7
	s_sext_i32_i16 s6, s7
	s_bfe_u32 s6, s6, 0x3001c
	s_add_i32 s13, s7, s6
	s_sext_i32_i16 s6, s13
	s_and_b32 s13, s13, 0xfff8
	s_sub_i32 s7, s7, s13
	s_sext_i32_i16 s7, s7
	s_lshr_b32 s6, s6, 3
	s_add_i32 s26, s12, s7
	s_ashr_i32 s27, s26, 31
	s_bfe_i64 s[14:15], s[6:7], 0x100000
	s_lshl_b64 s[12:13], s[26:27], 19
	s_lshl_b64 s[14:15], s[14:15], 19
	s_add_u32 s28, s37, s14
	s_addc_u32 s29, s39, s15
	s_add_i32 s27, s46, 0
	s_add_i32 m0, s27, 0x10000
	v_lshl_or_b32 v134, v0, 11, v1
	global_load_lds_dwordx4 v130, s[28:29]
	s_add_i32 m0, s27, 0x12000
	s_add_u32 s14, s28, 0x40000
	global_load_lds_dwordx4 v134, s[28:29]
	s_addc_u32 s15, s29, 0
	s_add_i32 m0, s27, 0x14000
	v_lshl_or_b32 v128, v4, 11, v1
	global_load_lds_dwordx4 v130, s[14:15]
	s_add_i32 m0, s27, 0x16000
	s_add_u32 s30, s3, s12
	s_addc_u32 s31, s36, s13
	s_add_i32 s49, s27, 0x2000
	global_load_lds_dwordx4 v134, s[14:15]
	s_mov_b32 m0, s27
	s_add_u32 s12, s30, 0x40000
	v_lshl_or_b32 v132, v3, 11, v1
	global_load_lds_dwordx4 v128, s[30:31]
	s_mov_b32 m0, s49
	s_addc_u32 s13, s31, 0
	s_add_i32 s50, s27, 0x4000
	global_load_lds_dwordx4 v132, s[30:31]
	s_mov_b32 m0, s50
	s_add_i32 s51, s27, 0x6000
	global_load_lds_dwordx4 v128, s[12:13]
	s_mov_b32 m0, s51
	v_mov_b32_e32 v131, 0
	global_load_lds_dwordx4 v132, s[12:13]
	v_mov_b32_e32 v135, v131
	v_mov_b32_e32 v129, v131
	v_mov_b32_e32 v133, v131
	s_cmp_eq_u32 s5, 1
	s_mov_b32 s52, 0
	v_lshl_add_u64 v[6:7], s[28:29], 0, v[130:131]
	v_lshl_add_u64 v[4:5], s[28:29], 0, v[134:135]
	v_lshl_add_u64 v[0:1], s[30:31], 0, v[128:129]
	s_cselect_b64 s[12:13], -1, 0
	s_cmp_lg_u32 s5, 1
	v_lshl_add_u64 v[2:3], s[30:31], 0, v[132:133]
	s_cbranch_scc1 .LBB0_869
	s_barrier

.LBB0_875:
	ds_read_b128 v[152:155], v149
	ds_read_b128 v[156:159], v149 offset:1024
	ds_read_b128 v[160:163], v149 offset:2048
	ds_read_b128 v[164:167], v149 offset:3072
	ds_read_b128 v[168:171], v150
	ds_read_b128 v[172:175], v150 offset:1024
	ds_read_b128 v[176:179], v150 offset:2048
	ds_read_b128 v[180:183], v150 offset:3072
	s_add_u32 s4, s28, 0xfffc0080
	s_addc_u32 s5, s29, -1
	s_cmp_eq_u32 s67, 12
	s_cselect_b32 s35, s21, s5
	s_cselect_b32 s34, s63, s4
	s_cselect_b32 s31, s19, s66
	s_cselect_b32 s30, s64, s65
	v_lshl_add_u64 v[144:145], s[28:29], 0, v[138:139]
	s_add_i32 m0, s27, 0xc000
	ds_read_b128 v[184:187], v151
	ds_read_b128 v[188:191], v151 offset:1024
	ds_read_b128 v[192:195], v151 offset:2048
	ds_read_b128 v[198:201], v151 offset:3072
	ds_read_b128 v[202:205], v151 offset:4096
	ds_read_b128 v[206:209], v151 offset:5120
	ds_read_b128 v[210:213], v151 offset:6144
	ds_read_b128 v[214:217], v151 offset:7168
	global_load_lds_dwordx4 v[144:145], off
	v_lshl_add_u64 v[144:145], s[28:29], 0, v[136:137]
	s_add_i32 m0, s27, 0xe000
	s_nop 0
	global_load_lds_dwordx4 v[144:145], off
	s_waitcnt vmcnt(8)
	s_waitcnt lgkmcnt(0)
	s_barrier
	s_waitcnt lgkmcnt(0)
	v_mfma_f32_16x16x32_bf16 v[124:127], v[152:155], v[184:187], v[124:127]
	v_mfma_f32_16x16x32_bf16 v[120:123], v[160:163], v[184:187], v[120:123]
	v_mfma_f32_16x16x32_bf16 v[116:119], v[152:155], v[192:195], v[116:119]
	v_mfma_f32_16x16x32_bf16 v[108:111], v[160:163], v[192:195], v[108:111]
	v_mfma_f32_16x16x32_bf16 v[100:103], v[152:155], v[202:205], v[100:103]
	v_mfma_f32_16x16x32_bf16 v[92:95], v[160:163], v[202:205], v[92:95]
	v_mfma_f32_16x16x32_bf16 v[84:87], v[152:155], v[210:213], v[84:87]
	v_mfma_f32_16x16x32_bf16 v[76:79], v[160:163], v[210:213], v[76:79]
	v_mfma_f32_16x16x32_bf16 v[124:127], v[156:159], v[188:191], v[124:127]
	v_mfma_f32_16x16x32_bf16 v[120:123], v[164:167], v[188:191], v[120:123]
	v_mfma_f32_16x16x32_bf16 v[116:119], v[156:159], v[198:201], v[116:119]
	v_mfma_f32_16x16x32_bf16 v[108:111], v[164:167], v[198:201], v[108:111]
	v_mfma_f32_16x16x32_bf16 v[100:103], v[156:159], v[206:209], v[100:103]
	v_mfma_f32_16x16x32_bf16 v[92:95], v[164:167], v[206:209], v[92:95]
	v_mfma_f32_16x16x32_bf16 v[84:87], v[156:159], v[214:217], v[84:87]
	v_mfma_f32_16x16x32_bf16 v[76:79], v[164:167], v[214:217], v[76:79]
	v_mfma_f32_16x16x32_bf16 v[112:115], v[168:171], v[184:187], v[112:115]
	v_mfma_f32_16x16x32_bf16 v[104:107], v[176:179], v[184:187], v[104:107]
	v_mfma_f32_16x16x32_bf16 v[96:99], v[168:171], v[192:195], v[96:99]
	v_mfma_f32_16x16x32_bf16 v[88:91], v[176:179], v[192:195], v[88:91]
	v_mfma_f32_16x16x32_bf16 v[80:83], v[168:171], v[202:205], v[80:83]
	v_mfma_f32_16x16x32_bf16 v[72:75], v[176:179], v[202:205], v[72:75]
	v_mfma_f32_16x16x32_bf16 v[68:71], v[168:171], v[210:213], v[68:71]
	v_mfma_f32_16x16x32_bf16 v[64:67], v[176:179], v[210:213], v[64:67]
	v_mfma_f32_16x16x32_bf16 v[112:115], v[172:175], v[188:191], v[112:115]
	v_mfma_f32_16x16x32_bf16 v[104:107], v[180:183], v[188:191], v[104:107]
	v_mfma_f32_16x16x32_bf16 v[96:99], v[172:175], v[198:201], v[96:99]
	v_mfma_f32_16x16x32_bf16 v[88:91], v[180:183], v[198:201], v[88:91]
	v_mfma_f32_16x16x32_bf16 v[80:83], v[172:175], v[206:209], v[80:83]
	v_mfma_f32_16x16x32_bf16 v[72:75], v[180:183], v[206:209], v[72:75]
	v_mfma_f32_16x16x32_bf16 v[68:71], v[172:175], v[214:217], v[68:71]
	v_mfma_f32_16x16x32_bf16 v[64:67], v[180:183], v[214:217], v[64:67]
	s_barrier
	s_add_i32 s4, s58, s46
	v_lshl_add_u64 v[144:145], s[30:31], 0, v[130:131]
	s_mov_b32 m0, s4
	ds_read_b128 v[184:187], v151 offset:16384
	ds_read_b128 v[188:191], v151 offset:17408
	ds_read_b128 v[192:195], v151 offset:18432
	ds_read_b128 v[198:201], v151 offset:19456
	ds_read_b128 v[202:205], v151 offset:20480
	ds_read_b128 v[206:209], v151 offset:21504
	ds_read_b128 v[210:213], v151 offset:22528
	ds_read_b128 v[214:217], v151 offset:23552
	global_load_lds_dwordx4 v[144:145], off
	s_add_i32 m0, s4, 0x2000
	s_add_u32 s4, s30, 0x40000
	v_lshl_add_u64 v[218:219], s[30:31], 0, v[134:135]
	s_addc_u32 s5, s31, 0
	s_add_i32 s33, s59, s46
	global_load_lds_dwordx4 v[218:219], off
	v_lshl_add_u64 v[220:221], s[4:5], 0, v[130:131]
	s_mov_b32 m0, s33
	v_lshl_add_u64 v[224:225], s[34:35], 0, v[132:133]
	global_load_lds_dwordx4 v[220:221], off
	v_lshl_add_u64 v[220:221], s[4:5], 0, v[134:135]
	s_add_i32 m0, s33, 0x2000
	s_nop 0
	global_load_lds_dwordx4 v[220:221], off
	v_lshl_add_u64 v[220:221], s[34:35], 0, v[128:129]
	s_mov_b32 m0, s27
	s_nop 0
	global_load_lds_dwordx4 v[220:221], off
	s_mov_b32 m0, s49
	s_nop 0
	global_load_lds_dwordx4 v[224:225], off
	s_waitcnt vmcnt(8)
	s_waitcnt lgkmcnt(0)
	s_barrier
	s_waitcnt lgkmcnt(0)
	v_mfma_f32_16x16x32_bf16 v[60:63], v[152:155], v[184:187], v[60:63]
	v_mfma_f32_16x16x32_bf16 v[56:59], v[160:163], v[184:187], v[56:59]
	v_mfma_f32_16x16x32_bf16 v[52:55], v[152:155], v[192:195], v[52:55]
	v_mfma_f32_16x16x32_bf16 v[44:47], v[160:163], v[192:195], v[44:47]
	v_mfma_f32_16x16x32_bf16 v[36:39], v[152:155], v[202:205], v[36:39]
	v_mfma_f32_16x16x32_bf16 v[28:31], v[160:163], v[202:205], v[28:31]
	v_mfma_f32_16x16x32_bf16 v[20:23], v[152:155], v[210:213], v[20:23]
	v_mfma_f32_16x16x32_bf16 v[12:15], v[160:163], v[210:213], v[12:15]
	v_mfma_f32_16x16x32_bf16 v[60:63], v[156:159], v[188:191], v[60:63]
	v_mfma_f32_16x16x32_bf16 v[56:59], v[164:167], v[188:191], v[56:59]
	v_mfma_f32_16x16x32_bf16 v[52:55], v[156:159], v[198:201], v[52:55]
	v_mfma_f32_16x16x32_bf16 v[44:47], v[164:167], v[198:201], v[44:47]
	v_mfma_f32_16x16x32_bf16 v[36:39], v[156:159], v[206:209], v[36:39]
	v_mfma_f32_16x16x32_bf16 v[28:31], v[164:167], v[206:209], v[28:31]
	v_mfma_f32_16x16x32_bf16 v[20:23], v[156:159], v[214:217], v[20:23]
	v_mfma_f32_16x16x32_bf16 v[12:15], v[164:167], v[214:217], v[12:15]
	v_mfma_f32_16x16x32_bf16 v[48:51], v[168:171], v[184:187], v[48:51]
	v_mfma_f32_16x16x32_bf16 v[40:43], v[176:179], v[184:187], v[40:43]
	v_mfma_f32_16x16x32_bf16 v[32:35], v[168:171], v[192:195], v[32:35]
	v_mfma_f32_16x16x32_bf16 v[24:27], v[176:179], v[192:195], v[24:27]
	v_mfma_f32_16x16x32_bf16 v[16:19], v[168:171], v[202:205], v[16:19]
	v_mfma_f32_16x16x32_bf16 v[8:11], v[176:179], v[202:205], v[8:11]
	v_mfma_f32_16x16x32_bf16 v[4:7], v[168:171], v[210:213], v[4:7]
	v_mfma_f32_16x16x32_bf16 v[0:3], v[176:179], v[210:213], v[0:3]
	v_mfma_f32_16x16x32_bf16 v[48:51], v[172:175], v[188:191], v[48:51]
	v_mfma_f32_16x16x32_bf16 v[40:43], v[180:183], v[188:191], v[40:43]
	v_mfma_f32_16x16x32_bf16 v[32:35], v[172:175], v[198:201], v[32:35]
	v_mfma_f32_16x16x32_bf16 v[24:27], v[180:183], v[198:201], v[24:27]
	v_mfma_f32_16x16x32_bf16 v[16:19], v[172:175], v[206:209], v[16:19]
	v_mfma_f32_16x16x32_bf16 v[8:11], v[180:183], v[206:209], v[8:11]
	v_mfma_f32_16x16x32_bf16 v[4:7], v[172:175], v[214:217], v[4:7]
	v_mfma_f32_16x16x32_bf16 v[0:3], v[180:183], v[214:217], v[0:3]
	s_barrier
	s_add_i32 s33, 0, 0x18000
	s_add_i32 s40, 0, 0x1c000
	v_add_u32_e32 v164, s33, v148
	v_add_u32_e32 v180, s40, v148
	ds_read_b128 v[152:155], v164
	ds_read_b128 v[156:159], v164 offset:1024
	ds_read_b128 v[160:163], v164 offset:2048
	ds_read_b128 v[164:167], v164 offset:3072
	ds_read_b128 v[168:171], v180
	ds_read_b128 v[172:175], v180 offset:1024
	ds_read_b128 v[176:179], v180 offset:2048
	ds_read_b128 v[180:183], v180 offset:3072
	s_add_u32 s4, s34, 0x40000
	s_addc_u32 s5, s35, 0
	s_mov_b32 m0, s50
	v_lshl_add_u64 v[226:227], s[4:5], 0, v[128:129]
	ds_read_b128 v[184:187], v151 offset:32768
	ds_read_b128 v[188:191], v151 offset:33792
	ds_read_b128 v[192:195], v151 offset:34816
	ds_read_b128 v[198:201], v151 offset:35840
	ds_read_b128 v[202:205], v151 offset:36864
	ds_read_b128 v[206:209], v151 offset:37888
	ds_read_b128 v[210:213], v151 offset:38912
	ds_read_b128 v[214:217], v151 offset:39936
	global_load_lds_dwordx4 v[226:227], off
	v_lshl_add_u64 v[226:227], s[4:5], 0, v[132:133]
	s_mov_b32 m0, s51
	s_nop 0
	global_load_lds_dwordx4 v[226:227], off
	s_waitcnt vmcnt(8)
	s_waitcnt lgkmcnt(0)
	s_barrier
	s_waitcnt lgkmcnt(0)
	v_mfma_f32_16x16x32_bf16 v[124:127], v[152:155], v[184:187], v[124:127]
	v_mfma_f32_16x16x32_bf16 v[120:123], v[160:163], v[184:187], v[120:123]
	v_mfma_f32_16x16x32_bf16 v[116:119], v[152:155], v[192:195], v[116:119]
	v_mfma_f32_16x16x32_bf16 v[108:111], v[160:163], v[192:195], v[108:111]
	v_mfma_f32_16x16x32_bf16 v[100:103], v[152:155], v[202:205], v[100:103]
	v_mfma_f32_16x16x32_bf16 v[92:95], v[160:163], v[202:205], v[92:95]
	v_mfma_f32_16x16x32_bf16 v[84:87], v[152:155], v[210:213], v[84:87]
	v_mfma_f32_16x16x32_bf16 v[76:79], v[160:163], v[210:213], v[76:79]
	v_mfma_f32_16x16x32_bf16 v[124:127], v[156:159], v[188:191], v[124:127]
	v_mfma_f32_16x16x32_bf16 v[120:123], v[164:167], v[188:191], v[120:123]
	v_mfma_f32_16x16x32_bf16 v[116:119], v[156:159], v[198:201], v[116:119]
	v_mfma_f32_16x16x32_bf16 v[108:111], v[164:167], v[198:201], v[108:111]
	v_mfma_f32_16x16x32_bf16 v[100:103], v[156:159], v[206:209], v[100:103]
	v_mfma_f32_16x16x32_bf16 v[92:95], v[164:167], v[206:209], v[92:95]
	v_mfma_f32_16x16x32_bf16 v[84:87], v[156:159], v[214:217], v[84:87]
	v_mfma_f32_16x16x32_bf16 v[76:79], v[164:167], v[214:217], v[76:79]
	v_mfma_f32_16x16x32_bf16 v[112:115], v[168:171], v[184:187], v[112:115]
	v_mfma_f32_16x16x32_bf16 v[104:107], v[176:179], v[184:187], v[104:107]
	v_mfma_f32_16x16x32_bf16 v[96:99], v[168:171], v[192:195], v[96:99]
	v_mfma_f32_16x16x32_bf16 v[88:91], v[176:179], v[192:195], v[88:91]
	v_mfma_f32_16x16x32_bf16 v[80:83], v[168:171], v[202:205], v[80:83]
	v_mfma_f32_16x16x32_bf16 v[72:75], v[176:179], v[202:205], v[72:75]
	v_mfma_f32_16x16x32_bf16 v[68:71], v[168:171], v[210:213], v[68:71]
	v_mfma_f32_16x16x32_bf16 v[64:67], v[176:179], v[210:213], v[64:67]
	v_mfma_f32_16x16x32_bf16 v[112:115], v[172:175], v[188:191], v[112:115]
	v_mfma_f32_16x16x32_bf16 v[104:107], v[180:183], v[188:191], v[104:107]
	v_mfma_f32_16x16x32_bf16 v[96:99], v[172:175], v[198:201], v[96:99]
	v_mfma_f32_16x16x32_bf16 v[88:91], v[180:183], v[198:201], v[88:91]
	v_mfma_f32_16x16x32_bf16 v[80:83], v[172:175], v[206:209], v[80:83]
	v_mfma_f32_16x16x32_bf16 v[72:75], v[180:183], v[206:209], v[72:75]
	v_mfma_f32_16x16x32_bf16 v[68:71], v[172:175], v[214:217], v[68:71]
	v_mfma_f32_16x16x32_bf16 v[64:67], v[180:183], v[214:217], v[64:67]
	s_barrier
	s_add_i32 s4, s33, s46
	v_lshl_add_u64 v[144:145], v[144:145], 0, s[14:15]
	s_mov_b32 m0, s4
	ds_read_b128 v[184:187], v151 offset:49152
	ds_read_b128 v[188:191], v151 offset:50176
	ds_read_b128 v[192:195], v151 offset:51200
	ds_read_b128 v[198:201], v151 offset:52224
	ds_read_b128 v[202:205], v151 offset:53248
	ds_read_b128 v[206:209], v151 offset:54272
	ds_read_b128 v[210:213], v151 offset:55296
	ds_read_b128 v[214:217], v151 offset:56320
	global_load_lds_dwordx4 v[144:145], off
	s_add_i32 m0, s4, 0x2000
	s_add_u32 s4, s30, 0x40080
	v_lshl_add_u64 v[144:145], v[218:219], 0, s[14:15]
	s_addc_u32 s5, s31, 0
	s_add_i32 s30, s40, s46
	global_load_lds_dwordx4 v[144:145], off
	v_lshl_add_u64 v[144:145], s[4:5], 0, v[130:131]
	s_mov_b32 m0, s30
	s_nop 0
	global_load_lds_dwordx4 v[144:145], off
	v_lshl_add_u64 v[144:145], s[4:5], 0, v[134:135]
	s_add_i32 m0, s30, 0x2000
	s_nop 0
	global_load_lds_dwordx4 v[144:145], off
	v_lshl_add_u64 v[144:145], v[220:221], 0, s[14:15]
	s_mov_b32 m0, s56
	s_nop 0
	global_load_lds_dwordx4 v[144:145], off
	v_lshl_add_u64 v[144:145], v[224:225], 0, s[14:15]
	s_mov_b32 m0, s57
	s_nop 0
	global_load_lds_dwordx4 v[144:145], off
	s_waitcnt vmcnt(8)
	s_waitcnt lgkmcnt(0)
	s_barrier
	s_waitcnt lgkmcnt(0)
	v_mfma_f32_16x16x32_bf16 v[60:63], v[152:155], v[184:187], v[60:63]
	v_mfma_f32_16x16x32_bf16 v[56:59], v[160:163], v[184:187], v[56:59]
	v_mfma_f32_16x16x32_bf16 v[52:55], v[152:155], v[192:195], v[52:55]
	v_mfma_f32_16x16x32_bf16 v[44:47], v[160:163], v[192:195], v[44:47]
	v_mfma_f32_16x16x32_bf16 v[36:39], v[152:155], v[202:205], v[36:39]
	v_mfma_f32_16x16x32_bf16 v[28:31], v[160:163], v[202:205], v[28:31]
	v_mfma_f32_16x16x32_bf16 v[20:23], v[152:155], v[210:213], v[20:23]
	v_mfma_f32_16x16x32_bf16 v[12:15], v[160:163], v[210:213], v[12:15]
	v_mfma_f32_16x16x32_bf16 v[60:63], v[156:159], v[188:191], v[60:63]
	v_mfma_f32_16x16x32_bf16 v[56:59], v[164:167], v[188:191], v[56:59]
	v_mfma_f32_16x16x32_bf16 v[52:55], v[156:159], v[198:201], v[52:55]
	v_mfma_f32_16x16x32_bf16 v[44:47], v[164:167], v[198:201], v[44:47]
	v_mfma_f32_16x16x32_bf16 v[36:39], v[156:159], v[206:209], v[36:39]
	v_mfma_f32_16x16x32_bf16 v[28:31], v[164:167], v[206:209], v[28:31]
	v_mfma_f32_16x16x32_bf16 v[20:23], v[156:159], v[214:217], v[20:23]
	v_mfma_f32_16x16x32_bf16 v[12:15], v[164:167], v[214:217], v[12:15]
	v_mfma_f32_16x16x32_bf16 v[48:51], v[168:171], v[184:187], v[48:51]
	v_mfma_f32_16x16x32_bf16 v[40:43], v[176:179], v[184:187], v[40:43]
	v_mfma_f32_16x16x32_bf16 v[32:35], v[168:171], v[192:195], v[32:35]
	v_mfma_f32_16x16x32_bf16 v[24:27], v[176:179], v[192:195], v[24:27]
	v_mfma_f32_16x16x32_bf16 v[16:19], v[168:171], v[202:205], v[16:19]
	v_mfma_f32_16x16x32_bf16 v[8:11], v[176:179], v[202:205], v[8:11]
	v_mfma_f32_16x16x32_bf16 v[4:7], v[168:171], v[210:213], v[4:7]
	v_mfma_f32_16x16x32_bf16 v[0:3], v[176:179], v[210:213], v[0:3]
	v_mfma_f32_16x16x32_bf16 v[48:51], v[172:175], v[188:191], v[48:51]
	v_mfma_f32_16x16x32_bf16 v[40:43], v[180:183], v[188:191], v[40:43]
	v_mfma_f32_16x16x32_bf16 v[32:35], v[172:175], v[198:201], v[32:35]
	v_mfma_f32_16x16x32_bf16 v[24:27], v[180:183], v[198:201], v[24:27]
	v_mfma_f32_16x16x32_bf16 v[16:19], v[172:175], v[206:209], v[16:19]
	v_mfma_f32_16x16x32_bf16 v[8:11], v[180:183], v[206:209], v[8:11]
	v_mfma_f32_16x16x32_bf16 v[4:7], v[172:175], v[214:217], v[4:7]
	v_mfma_f32_16x16x32_bf16 v[0:3], v[180:183], v[214:217], v[0:3]
	s_barrier
	s_add_i32 s67, s67, 2
	s_add_u32 s65, s65, 0x100
	s_addc_u32 s66, s66, 0
	s_add_u32 s28, s28, 0x100
	s_addc_u32 s29, s29, 0
	s_cmp_gt_u32 s67, 13
	s_cbranch_scc0 .LBB0_875
	s_and_b64 vcc, exec, s[16:17]
	s_cbranch_vccz .LBB0_878
	s_barrier

.LBB0_882:
	s_setprio 0
	s_cmp_gt_i32 s77, 11
	s_cselect_b64 s[46:47], -1, 0
	s_and_b64 s[4:5], s[8:9], s[46:47]
	s_andn2_b64 vcc, exec, s[4:5]
	s_cbranch_vccnz .LBB0_928
	s_waitcnt vmcnt(0)
	s_waitcnt vmcnt(0) lgkmcnt(0)
	s_barrier
	s_and_saveexec_b64 s[48:49], s[82:83]
	s_cbranch_execz .LBB0_927
	s_add_i32 s3, 0, 0x20000
	v_mov_b32_e32 v0, s3
	s_waitcnt vmcnt(0) expcnt(0) lgkmcnt(0)
	ds_read_b32 v2, v0
	s_add_i32 s3, 0, 0x20004
	v_mov_b32_e32 v0, s3
	ds_read_b32 v0, v0
	s_waitcnt lgkmcnt(1)
	v_cmp_ne_u32_e32 vcc, 0, v2
	s_cbranch_vccnz .LBB0_898
	s_add_u32 s6, s42, 0x51fda00
	s_addc_u32 s7, s43, 0
	s_add_u32 s10, s42, 0x51fdc00
	s_addc_u32 s11, s43, 0
	s_add_u32 s12, s42, 0x51fdd00
	s_addc_u32 s13, s43, 0
	s_add_u32 s14, s42, 0x51fde00
	s_addc_u32 s15, s43, 0
	s_add_u32 s16, s42, 0x51fdf00
	s_addc_u32 s17, s43, 0
	s_add_u32 s18, s42, 0x51fe000
	s_addc_u32 s19, s43, 0
	s_add_u32 s20, s42, 0x51fe100
	s_addc_u32 s21, s43, 0
	s_add_u32 s22, s42, 0x51fe200
	s_addc_u32 s23, s43, 0
	s_add_u32 s24, s42, 0x51fe300
	s_addc_u32 s25, s43, 0
	s_add_u32 s26, s42, 0x51fe400
	s_addc_u32 s27, s43, 0
	s_add_u32 s28, s42, 0x51fe500
	s_addc_u32 s29, s43, 0
	s_add_u32 s30, s42, 0x51fe600
	s_addc_u32 s31, s43, 0
	s_add_u32 s34, s42, 0x51fe700
	s_addc_u32 s35, s43, 0
	s_add_u32 s36, s42, 0x51fe800
	s_addc_u32 s37, s43, 0
	s_load_dwordx2 s[4:5], s[80:81], 0x4
	s_add_u32 s40, s42, 0x51fe900
	s_addc_u32 s41, s43, 0
	s_add_u32 s44, s42, 0x51fea00
	s_addc_u32 s45, s43, 0
	s_add_u32 s50, s42, 0x51feb00
	s_waitcnt lgkmcnt(0)
	s_mul_i32 s3, s4, s38
	s_addc_u32 s51, s43, 0
	s_mul_i32 s3, s3, s5
	s_mov_b32 s4, 1
	s_mov_b64 s[8:9], 0
	v_mov_b64_e32 v[0:1], s[10:11]
	v_mov_b64_e32 v[2:3], s[12:13]
	v_mov_b64_e32 v[4:5], s[14:15]
	v_mov_b64_e32 v[6:7], s[16:17]
	v_mov_b64_e32 v[8:9], s[18:19]
	v_mov_b64_e32 v[10:11], s[20:21]
	v_mov_b64_e32 v[12:13], s[22:23]
	v_mov_b64_e32 v[14:15], s[24:25]
	v_mov_b64_e32 v[16:17], s[26:27]
	v_mov_b64_e32 v[18:19], s[28:29]
	v_mov_b64_e32 v[20:21], s[30:31]
	v_mov_b64_e32 v[22:23], s[34:35]
	v_mov_b64_e32 v[24:25], s[36:37]
	v_mov_b64_e32 v[26:27], s[40:41]
	v_mov_b64_e32 v[28:29], s[44:45]
	v_mov_b64_e32 v[30:31], s[50:51]
	s_branch .LBB0_888

.LBB0_1025:
	s_cmp_lt_i32 s76, 13
	s_cselect_b64 s[12:13], -1, 0
	s_and_b64 s[4:5], s[12:13], s[46:47]
	s_andn2_b64 vcc, exec, s[4:5]
	s_cbranch_vccnz .LBB0_1050
	s_cmpk_gt_i32 s2, 0x3ff
	s_mov_b64 s[6:7], s[0:1]
	v_readfirstlane_b32 s20, v196
	s_waitcnt vmcnt(0) lgkmcnt(0)
	s_barrier
	s_cbranch_scc1 .LBB0_1050
	s_lshr_b32 s99, s20, 8
	s_cmp_eq_u32 s99, 1
	s_cbranch_scc0 .Lprio_p12
	s_setprio 1
.Lprio_p12:
	v_lshrrev_b32_e32 v1, 1, v196
	v_lshrrev_b32_e32 v2, 5, v196
	v_and_b32_e32 v1, 24, v1
	v_and_b32_e32 v2, 4, v2
	v_or3_b32 v1, v2, v223, v1
	v_lshrrev_b32_e32 v2, 3, v196
	s_movk_i32 s3, 0x70
	s_load_dwordx4 s[8:11], s[6:7], 0xd8
	v_lshlrev_b32_e32 v0, 4, v196
	v_and_or_b32 v3, v2, s3, v222
	s_movk_i32 s3, 0x60
	v_mul_u32_u24_e32 v8, 0xb00, v3
	v_add_u32_e32 v3, 0x2000, v0
	v_and_or_b32 v2, v2, s3, v1
	v_lshrrev_b32_e32 v3, 7, v3
	s_movk_i32 s3, 0xf0
	v_and_or_b32 v4, v3, s3, v222
	s_movk_i32 s3, 0xe0
	v_and_or_b32 v1, v3, s3, v1
	s_waitcnt lgkmcnt(0)
	s_add_u32 s3, s10, 0x23200e00
	s_addc_u32 s30, s11, 0
	s_add_u32 s31, s10, 0x2100000
	s_addc_u32 s34, s11, 0
	s_ashr_i32 s36, s2, 31
	s_lshr_b32 s4, s36, 29
	s_add_i32 s4, s2, s4
	s_ashr_i32 s7, s4, 3
	s_and_b32 s4, s4, -8
	s_lshr_b32 s5, s20, 6
	s_sub_i32 s4, s2, s4
	s_lshr_b32 s6, s20, 8
	s_lshl_b32 s35, s5, 10
	s_lshl_b32 s15, s4, 7
	s_mul_i32 s14, s4, 0x81
	s_cmp_lt_i32 s4, 0
	s_cselect_b32 s4, s14, s15
	s_add_i32 s4, s4, s7
	s_ashr_i32 s7, s4, 31
	s_lshr_b32 s7, s7, 27
	s_add_i32 s7, s4, s7
	s_ashr_i32 s14, s7, 5
	s_and_b32 s7, s7, 0xffe0
	s_sub_i32 s7, s4, s7
	s_bfe_i32 s4, s7, 0x80000
	s_bfe_u32 s4, s4, 0x3000c
	s_add_i32 s15, s7, s4
	s_bfe_i32 s4, s15, 0x80000
	s_and_b32 s15, s15, 0xf8
	v_and_b32_e32 v3, 32, v196
	s_sext_i32_i16 s16, s4
	s_sub_i32 s7, s7, s15
	v_bitop3_b32 v10, v0, v3, 48 bitop3:0x6c
	v_and_b32_e32 v11, 64, v196
	s_lshl_b32 s14, s14, 3
	s_lshr_b32 s4, s16, 3
	s_sext_i32_i8 s7, s7
	s_ashr_i32 s16, s16, 3
	v_or_b32_e32 v0, v10, v11
	s_add_i32 s14, s14, s7
	s_mul_hi_i32 s17, s16, 0x160000
	s_mul_i32 s16, s16, 0x160000
	v_mul_u32_u24_e32 v2, 0xb00, v2
	v_lshrrev_b32_e32 v0, 1, v0
	s_add_u32 s24, s31, s16
	v_or_b32_e32 v2, v2, v0
	s_addc_u32 s25, s34, s17
	s_add_i32 s37, s35, 0
	v_mul_u32_u24_e32 v9, 0xb00, v4
	v_mul_u32_u24_e32 v1, 0xb00, v1
	v_lshlrev_b32_e32 v186, 1, v2
	s_add_i32 m0, s37, 0x10000
	v_or_b32_e32 v3, v0, v8
	v_or_b32_e32 v2, v9, v0
	v_or_b32_e32 v0, v1, v0
	global_load_lds_dwordx4 v186, s[24:25]
	s_add_i32 m0, s37, 0x12000
	v_lshlrev_b32_e32 v190, 1, v0
	s_add_u32 s16, s24, 0xb0000
	global_load_lds_dwordx4 v190, s[24:25]
	s_addc_u32 s17, s25, 0
	s_add_i32 m0, s37, 0x14000
	s_mul_i32 s15, s14, 0x160000
	global_load_lds_dwordx4 v186, s[16:17]
	s_add_i32 m0, s37, 0x16000
	s_mul_hi_i32 s7, s14, 0x160000
	s_add_u32 s26, s3, s15
	s_addc_u32 s27, s30, s7
	s_add_i32 s39, s37, 0x2000
	v_lshlrev_b32_e32 v184, 1, v3
	global_load_lds_dwordx4 v190, s[16:17]
	s_mov_b32 m0, s37
	s_add_u32 s16, s26, 0xb0000
	v_lshlrev_b32_e32 v188, 1, v2
	global_load_lds_dwordx4 v184, s[26:27]
	s_mov_b32 m0, s39
	s_addc_u32 s17, s27, 0
	s_add_i32 s46, s37, 0x4000
	global_load_lds_dwordx4 v188, s[26:27]
	s_mov_b32 m0, s46
	s_add_i32 s47, s37, 0x6000
	global_load_lds_dwordx4 v184, s[16:17]
	s_mov_b32 m0, s47
	v_mov_b32_e32 v187, 0
	global_load_lds_dwordx4 v188, s[16:17]
	v_mov_b32_e32 v191, v187
	v_mov_b32_e32 v185, v187
	v_mov_b32_e32 v189, v187
	s_cmp_eq_u32 s6, 1
	s_mov_b32 s15, 0
	v_lshl_add_u64 v[6:7], s[24:25], 0, v[186:187]
	v_lshl_add_u64 v[4:5], s[24:25], 0, v[190:191]
	v_lshl_add_u64 v[0:1], s[26:27], 0, v[184:185]
	s_cselect_b64 s[16:17], -1, 0
	s_cmp_lg_u32 s6, 1
	v_lshl_add_u64 v[2:3], s[26:27], 0, v[188:189]
	s_cbranch_scc1 .LBB0_1029
	s_barrier

.LBB0_1043:
	ds_read_b128 v[128:131], v217
	ds_read_b128 v[132:135], v217 offset:1024
	ds_read_b128 v[136:139], v217 offset:2048
	ds_read_b128 v[140:143], v217 offset:3072
	ds_read_b128 v[144:147], v218
	ds_read_b128 v[148:151], v218 offset:1024
	ds_read_b128 v[152:155], v218 offset:2048
	ds_read_b128 v[156:159], v218 offset:3072
	s_add_u32 s4, s24, 0xfff50080
	s_addc_u32 s5, s25, -1
	s_cmp_eq_u32 s65, 40
	s_cselect_b32 s29, s9, s5
	s_cselect_b32 s28, s8, s4
	s_cselect_b32 s27, s23, s64
	s_cselect_b32 s26, s22, s63
	v_lshl_add_u64 v[210:211], s[24:25], 0, v[194:195]
	s_add_i32 m0, s37, 0xc000
	ds_read_b128 v[160:163], v219
	ds_read_b128 v[164:167], v219 offset:1024
	ds_read_b128 v[168:171], v219 offset:2048
	ds_read_b128 v[172:175], v219 offset:3072
	ds_read_b128 v[176:179], v219 offset:4096
	ds_read_b128 v[180:183], v219 offset:5120
	ds_read_b128 v[202:205], v219 offset:6144
	ds_read_b128 v[206:209], v219 offset:7168
	global_load_lds_dwordx4 v[210:211], off
	v_lshl_add_u64 v[210:211], s[24:25], 0, v[192:193]
	s_add_i32 m0, s37, 0xe000
	s_nop 0
	global_load_lds_dwordx4 v[210:211], off
	s_waitcnt vmcnt(8)
	s_waitcnt lgkmcnt(0)
	s_barrier
	s_waitcnt lgkmcnt(0)
	v_mfma_f32_16x16x32_bf16 v[124:127], v[128:131], v[160:163], v[124:127]
	v_mfma_f32_16x16x32_bf16 v[120:123], v[136:139], v[160:163], v[120:123]
	v_mfma_f32_16x16x32_bf16 v[108:111], v[128:131], v[168:171], v[108:111]
	v_mfma_f32_16x16x32_bf16 v[104:107], v[136:139], v[168:171], v[104:107]
	v_mfma_f32_16x16x32_bf16 v[92:95], v[128:131], v[176:179], v[92:95]
	v_mfma_f32_16x16x32_bf16 v[88:91], v[136:139], v[176:179], v[88:91]
	v_mfma_f32_16x16x32_bf16 v[76:79], v[128:131], v[202:205], v[76:79]
	v_mfma_f32_16x16x32_bf16 v[72:75], v[136:139], v[202:205], v[72:75]
	v_mfma_f32_16x16x32_bf16 v[124:127], v[132:135], v[164:167], v[124:127]
	v_mfma_f32_16x16x32_bf16 v[120:123], v[140:143], v[164:167], v[120:123]
	v_mfma_f32_16x16x32_bf16 v[108:111], v[132:135], v[172:175], v[108:111]
	v_mfma_f32_16x16x32_bf16 v[104:107], v[140:143], v[172:175], v[104:107]
	v_mfma_f32_16x16x32_bf16 v[92:95], v[132:135], v[180:183], v[92:95]
	v_mfma_f32_16x16x32_bf16 v[88:91], v[140:143], v[180:183], v[88:91]
	v_mfma_f32_16x16x32_bf16 v[76:79], v[132:135], v[206:209], v[76:79]
	v_mfma_f32_16x16x32_bf16 v[72:75], v[140:143], v[206:209], v[72:75]
	v_mfma_f32_16x16x32_bf16 v[116:119], v[144:147], v[160:163], v[116:119]
	v_mfma_f32_16x16x32_bf16 v[112:115], v[152:155], v[160:163], v[112:115]
	v_mfma_f32_16x16x32_bf16 v[100:103], v[144:147], v[168:171], v[100:103]
	v_mfma_f32_16x16x32_bf16 v[96:99], v[152:155], v[168:171], v[96:99]
	v_mfma_f32_16x16x32_bf16 v[84:87], v[144:147], v[176:179], v[84:87]
	v_mfma_f32_16x16x32_bf16 v[80:83], v[152:155], v[176:179], v[80:83]
	v_mfma_f32_16x16x32_bf16 v[68:71], v[144:147], v[202:205], v[68:71]
	v_mfma_f32_16x16x32_bf16 v[64:67], v[152:155], v[202:205], v[64:67]
	v_mfma_f32_16x16x32_bf16 v[116:119], v[148:151], v[164:167], v[116:119]
	v_mfma_f32_16x16x32_bf16 v[112:115], v[156:159], v[164:167], v[112:115]
	v_mfma_f32_16x16x32_bf16 v[100:103], v[148:151], v[172:175], v[100:103]
	v_mfma_f32_16x16x32_bf16 v[96:99], v[156:159], v[172:175], v[96:99]
	v_mfma_f32_16x16x32_bf16 v[84:87], v[148:151], v[180:183], v[84:87]
	v_mfma_f32_16x16x32_bf16 v[80:83], v[156:159], v[180:183], v[80:83]
	v_mfma_f32_16x16x32_bf16 v[68:71], v[148:151], v[206:209], v[68:71]
	v_mfma_f32_16x16x32_bf16 v[64:67], v[156:159], v[206:209], v[64:67]
	s_barrier
	s_add_i32 s4, s57, s35
	v_lshl_add_u64 v[210:211], s[26:27], 0, v[186:187]
	s_mov_b32 m0, s4
	ds_read_b128 v[160:163], v219 offset:16384
	ds_read_b128 v[164:167], v219 offset:17408
	ds_read_b128 v[168:171], v219 offset:18432
	ds_read_b128 v[172:175], v219 offset:19456
	ds_read_b128 v[176:179], v219 offset:20480
	ds_read_b128 v[180:183], v219 offset:21504
	ds_read_b128 v[202:205], v219 offset:22528
	ds_read_b128 v[206:209], v219 offset:23552
	global_load_lds_dwordx4 v[210:211], off
	s_add_i32 m0, s4, 0x2000
	s_add_u32 s4, s26, 0xb0000
	v_lshl_add_u64 v[212:213], s[26:27], 0, v[190:191]
	s_addc_u32 s5, s27, 0
	s_add_i32 s33, s58, s35
	global_load_lds_dwordx4 v[212:213], off
	v_lshl_add_u64 v[220:221], s[4:5], 0, v[186:187]
	s_mov_b32 m0, s33
	v_lshl_add_u64 v[222:223], s[28:29], 0, v[188:189]
	global_load_lds_dwordx4 v[220:221], off
	v_lshl_add_u64 v[220:221], s[4:5], 0, v[190:191]
	s_add_i32 m0, s33, 0x2000
	s_nop 0
	global_load_lds_dwordx4 v[220:221], off
	v_lshl_add_u64 v[220:221], s[28:29], 0, v[184:185]
	s_mov_b32 m0, s37
	s_nop 0
	global_load_lds_dwordx4 v[220:221], off
	s_mov_b32 m0, s39
	s_nop 0
	global_load_lds_dwordx4 v[222:223], off
	s_waitcnt vmcnt(8)
	s_waitcnt lgkmcnt(0)
	s_barrier
	s_waitcnt lgkmcnt(0)
	v_mfma_f32_16x16x32_bf16 v[60:63], v[128:131], v[160:163], v[60:63]
	v_mfma_f32_16x16x32_bf16 v[56:59], v[136:139], v[160:163], v[56:59]
	v_mfma_f32_16x16x32_bf16 v[44:47], v[128:131], v[168:171], v[44:47]
	v_mfma_f32_16x16x32_bf16 v[40:43], v[136:139], v[168:171], v[40:43]
	v_mfma_f32_16x16x32_bf16 v[28:31], v[128:131], v[176:179], v[28:31]
	v_mfma_f32_16x16x32_bf16 v[24:27], v[136:139], v[176:179], v[24:27]
	v_mfma_f32_16x16x32_bf16 v[12:15], v[128:131], v[202:205], v[12:15]
	v_mfma_f32_16x16x32_bf16 v[8:11], v[136:139], v[202:205], v[8:11]
	v_mfma_f32_16x16x32_bf16 v[60:63], v[132:135], v[164:167], v[60:63]
	v_mfma_f32_16x16x32_bf16 v[56:59], v[140:143], v[164:167], v[56:59]
	v_mfma_f32_16x16x32_bf16 v[44:47], v[132:135], v[172:175], v[44:47]
	v_mfma_f32_16x16x32_bf16 v[40:43], v[140:143], v[172:175], v[40:43]
	v_mfma_f32_16x16x32_bf16 v[28:31], v[132:135], v[180:183], v[28:31]
	v_mfma_f32_16x16x32_bf16 v[24:27], v[140:143], v[180:183], v[24:27]
	v_mfma_f32_16x16x32_bf16 v[12:15], v[132:135], v[206:209], v[12:15]
	v_mfma_f32_16x16x32_bf16 v[8:11], v[140:143], v[206:209], v[8:11]
	v_mfma_f32_16x16x32_bf16 v[52:55], v[144:147], v[160:163], v[52:55]
	v_mfma_f32_16x16x32_bf16 v[48:51], v[152:155], v[160:163], v[48:51]
	v_mfma_f32_16x16x32_bf16 v[36:39], v[144:147], v[168:171], v[36:39]
	v_mfma_f32_16x16x32_bf16 v[32:35], v[152:155], v[168:171], v[32:35]
	v_mfma_f32_16x16x32_bf16 v[20:23], v[144:147], v[176:179], v[20:23]
	v_mfma_f32_16x16x32_bf16 v[16:19], v[152:155], v[176:179], v[16:19]
	v_mfma_f32_16x16x32_bf16 v[4:7], v[144:147], v[202:205], v[4:7]
	v_mfma_f32_16x16x32_bf16 v[0:3], v[152:155], v[202:205], v[0:3]
	v_mfma_f32_16x16x32_bf16 v[52:55], v[148:151], v[164:167], v[52:55]
	v_mfma_f32_16x16x32_bf16 v[48:51], v[156:159], v[164:167], v[48:51]
	v_mfma_f32_16x16x32_bf16 v[36:39], v[148:151], v[172:175], v[36:39]
	v_mfma_f32_16x16x32_bf16 v[32:35], v[156:159], v[172:175], v[32:35]
	v_mfma_f32_16x16x32_bf16 v[20:23], v[148:151], v[180:183], v[20:23]
	v_mfma_f32_16x16x32_bf16 v[16:19], v[156:159], v[180:183], v[16:19]
	v_mfma_f32_16x16x32_bf16 v[4:7], v[148:151], v[206:209], v[4:7]
	v_mfma_f32_16x16x32_bf16 v[0:3], v[156:159], v[206:209], v[0:3]
	s_barrier
	s_add_i32 s33, 0, 0x18000
	s_add_i32 s40, 0, 0x1c000
	v_add_u32_e32 v140, s33, v216
	v_add_u32_e32 v156, s40, v216
	ds_read_b128 v[128:131], v140
	ds_read_b128 v[132:135], v140 offset:1024
	ds_read_b128 v[136:139], v140 offset:2048
	ds_read_b128 v[140:143], v140 offset:3072
	ds_read_b128 v[144:147], v156
	ds_read_b128 v[148:151], v156 offset:1024
	ds_read_b128 v[152:155], v156 offset:2048
	ds_read_b128 v[156:159], v156 offset:3072
	s_add_u32 s4, s28, 0xb0000
	s_addc_u32 s5, s29, 0
	s_mov_b32 m0, s46
	v_lshl_add_u64 v[224:225], s[4:5], 0, v[184:185]
	ds_read_b128 v[160:163], v219 offset:32768
	ds_read_b128 v[164:167], v219 offset:33792
	ds_read_b128 v[168:171], v219 offset:34816
	ds_read_b128 v[172:175], v219 offset:35840
	ds_read_b128 v[176:179], v219 offset:36864
	ds_read_b128 v[180:183], v219 offset:37888
	ds_read_b128 v[202:205], v219 offset:38912
	ds_read_b128 v[206:209], v219 offset:39936
	global_load_lds_dwordx4 v[224:225], off
	v_lshl_add_u64 v[224:225], s[4:5], 0, v[188:189]
	s_mov_b32 m0, s47
	s_nop 0
	global_load_lds_dwordx4 v[224:225], off
	s_waitcnt vmcnt(8)
	s_waitcnt lgkmcnt(0)
	s_barrier
	s_waitcnt lgkmcnt(0)
	v_mfma_f32_16x16x32_bf16 v[124:127], v[128:131], v[160:163], v[124:127]
	v_mfma_f32_16x16x32_bf16 v[120:123], v[136:139], v[160:163], v[120:123]
	v_mfma_f32_16x16x32_bf16 v[108:111], v[128:131], v[168:171], v[108:111]
	v_mfma_f32_16x16x32_bf16 v[104:107], v[136:139], v[168:171], v[104:107]
	v_mfma_f32_16x16x32_bf16 v[92:95], v[128:131], v[176:179], v[92:95]
	v_mfma_f32_16x16x32_bf16 v[88:91], v[136:139], v[176:179], v[88:91]
	v_mfma_f32_16x16x32_bf16 v[76:79], v[128:131], v[202:205], v[76:79]
	v_mfma_f32_16x16x32_bf16 v[72:75], v[136:139], v[202:205], v[72:75]
	v_mfma_f32_16x16x32_bf16 v[124:127], v[132:135], v[164:167], v[124:127]
	v_mfma_f32_16x16x32_bf16 v[120:123], v[140:143], v[164:167], v[120:123]
	v_mfma_f32_16x16x32_bf16 v[108:111], v[132:135], v[172:175], v[108:111]
	v_mfma_f32_16x16x32_bf16 v[104:107], v[140:143], v[172:175], v[104:107]
	v_mfma_f32_16x16x32_bf16 v[92:95], v[132:135], v[180:183], v[92:95]
	v_mfma_f32_16x16x32_bf16 v[88:91], v[140:143], v[180:183], v[88:91]
	v_mfma_f32_16x16x32_bf16 v[76:79], v[132:135], v[206:209], v[76:79]
	v_mfma_f32_16x16x32_bf16 v[72:75], v[140:143], v[206:209], v[72:75]
	v_mfma_f32_16x16x32_bf16 v[116:119], v[144:147], v[160:163], v[116:119]
	v_mfma_f32_16x16x32_bf16 v[112:115], v[152:155], v[160:163], v[112:115]
	v_mfma_f32_16x16x32_bf16 v[100:103], v[144:147], v[168:171], v[100:103]
	v_mfma_f32_16x16x32_bf16 v[96:99], v[152:155], v[168:171], v[96:99]
	v_mfma_f32_16x16x32_bf16 v[84:87], v[144:147], v[176:179], v[84:87]
	v_mfma_f32_16x16x32_bf16 v[80:83], v[152:155], v[176:179], v[80:83]
	v_mfma_f32_16x16x32_bf16 v[68:71], v[144:147], v[202:205], v[68:71]
	v_mfma_f32_16x16x32_bf16 v[64:67], v[152:155], v[202:205], v[64:67]
	v_mfma_f32_16x16x32_bf16 v[116:119], v[148:151], v[164:167], v[116:119]
	v_mfma_f32_16x16x32_bf16 v[112:115], v[156:159], v[164:167], v[112:115]
	v_mfma_f32_16x16x32_bf16 v[100:103], v[148:151], v[172:175], v[100:103]
	v_mfma_f32_16x16x32_bf16 v[96:99], v[156:159], v[172:175], v[96:99]
	v_mfma_f32_16x16x32_bf16 v[84:87], v[148:151], v[180:183], v[84:87]
	v_mfma_f32_16x16x32_bf16 v[80:83], v[156:159], v[180:183], v[80:83]
	v_mfma_f32_16x16x32_bf16 v[68:71], v[148:151], v[206:209], v[68:71]
	v_mfma_f32_16x16x32_bf16 v[64:67], v[156:159], v[206:209], v[64:67]
	s_barrier
	s_add_i32 s4, s33, s35
	v_lshl_add_u64 v[210:211], v[210:211], 0, s[10:11]
	s_mov_b32 m0, s4
	ds_read_b128 v[160:163], v219 offset:49152
	ds_read_b128 v[164:167], v219 offset:50176
	ds_read_b128 v[168:171], v219 offset:51200
	ds_read_b128 v[172:175], v219 offset:52224
	ds_read_b128 v[176:179], v219 offset:53248
	ds_read_b128 v[180:183], v219 offset:54272
	ds_read_b128 v[202:205], v219 offset:55296
	ds_read_b128 v[206:209], v219 offset:56320
	global_load_lds_dwordx4 v[210:211], off
	s_add_i32 m0, s4, 0x2000
	s_add_u32 s4, s26, 0xb0080
	v_lshl_add_u64 v[210:211], v[212:213], 0, s[10:11]
	s_addc_u32 s5, s27, 0
	s_add_i32 s26, s40, s35
	global_load_lds_dwordx4 v[210:211], off
	v_lshl_add_u64 v[210:211], s[4:5], 0, v[186:187]
	s_mov_b32 m0, s26
	s_nop 0
	global_load_lds_dwordx4 v[210:211], off
	v_lshl_add_u64 v[210:211], s[4:5], 0, v[190:191]
	s_add_i32 m0, s26, 0x2000
	s_nop 0
	global_load_lds_dwordx4 v[210:211], off
	v_lshl_add_u64 v[210:211], v[220:221], 0, s[10:11]
	s_mov_b32 m0, s53
	s_nop 0
	global_load_lds_dwordx4 v[210:211], off
	v_lshl_add_u64 v[210:211], v[222:223], 0, s[10:11]
	s_mov_b32 m0, s54
	s_nop 0
	global_load_lds_dwordx4 v[210:211], off
	s_waitcnt vmcnt(8)
	s_waitcnt lgkmcnt(0)
	s_barrier
	s_waitcnt lgkmcnt(0)
	v_mfma_f32_16x16x32_bf16 v[60:63], v[128:131], v[160:163], v[60:63]
	v_mfma_f32_16x16x32_bf16 v[56:59], v[136:139], v[160:163], v[56:59]
	v_mfma_f32_16x16x32_bf16 v[44:47], v[128:131], v[168:171], v[44:47]
	v_mfma_f32_16x16x32_bf16 v[40:43], v[136:139], v[168:171], v[40:43]
	v_mfma_f32_16x16x32_bf16 v[28:31], v[128:131], v[176:179], v[28:31]
	v_mfma_f32_16x16x32_bf16 v[24:27], v[136:139], v[176:179], v[24:27]
	v_mfma_f32_16x16x32_bf16 v[12:15], v[128:131], v[202:205], v[12:15]
	v_mfma_f32_16x16x32_bf16 v[8:11], v[136:139], v[202:205], v[8:11]
	v_mfma_f32_16x16x32_bf16 v[60:63], v[132:135], v[164:167], v[60:63]
	v_mfma_f32_16x16x32_bf16 v[56:59], v[140:143], v[164:167], v[56:59]
	v_mfma_f32_16x16x32_bf16 v[44:47], v[132:135], v[172:175], v[44:47]
	v_mfma_f32_16x16x32_bf16 v[40:43], v[140:143], v[172:175], v[40:43]
	v_mfma_f32_16x16x32_bf16 v[28:31], v[132:135], v[180:183], v[28:31]
	v_mfma_f32_16x16x32_bf16 v[24:27], v[140:143], v[180:183], v[24:27]
	v_mfma_f32_16x16x32_bf16 v[12:15], v[132:135], v[206:209], v[12:15]
	v_mfma_f32_16x16x32_bf16 v[8:11], v[140:143], v[206:209], v[8:11]
	v_mfma_f32_16x16x32_bf16 v[52:55], v[144:147], v[160:163], v[52:55]
	v_mfma_f32_16x16x32_bf16 v[48:51], v[152:155], v[160:163], v[48:51]
	v_mfma_f32_16x16x32_bf16 v[36:39], v[144:147], v[168:171], v[36:39]
	v_mfma_f32_16x16x32_bf16 v[32:35], v[152:155], v[168:171], v[32:35]
	v_mfma_f32_16x16x32_bf16 v[20:23], v[144:147], v[176:179], v[20:23]
	v_mfma_f32_16x16x32_bf16 v[16:19], v[152:155], v[176:179], v[16:19]
	v_mfma_f32_16x16x32_bf16 v[4:7], v[144:147], v[202:205], v[4:7]
	v_mfma_f32_16x16x32_bf16 v[0:3], v[152:155], v[202:205], v[0:3]
	v_mfma_f32_16x16x32_bf16 v[52:55], v[148:151], v[164:167], v[52:55]
	v_mfma_f32_16x16x32_bf16 v[48:51], v[156:159], v[164:167], v[48:51]
	v_mfma_f32_16x16x32_bf16 v[36:39], v[148:151], v[172:175], v[36:39]
	v_mfma_f32_16x16x32_bf16 v[32:35], v[156:159], v[172:175], v[32:35]
	v_mfma_f32_16x16x32_bf16 v[20:23], v[148:151], v[180:183], v[20:23]
	v_mfma_f32_16x16x32_bf16 v[16:19], v[156:159], v[180:183], v[16:19]
	v_mfma_f32_16x16x32_bf16 v[4:7], v[148:151], v[206:209], v[4:7]
	v_mfma_f32_16x16x32_bf16 v[0:3], v[156:159], v[206:209], v[0:3]
	s_barrier
	s_add_i32 s65, s65, 2
	s_add_u32 s63, s63, 0x100
	s_addc_u32 s64, s64, 0
	s_add_u32 s24, s24, 0x100
	s_addc_u32 s25, s25, 0
	s_cmp_gt_u32 s65, 41
	s_cbranch_scc0 .LBB0_1043
	s_and_b64 vcc, exec, s[20:21]
	s_cbranch_vccz .LBB0_1046
	s_barrier

.LBB0_1050:
	s_setprio 0
	s_cmp_gt_i32 s77, 13
	s_cselect_b64 s[36:37], -1, 0
	s_and_b64 s[4:5], s[12:13], s[36:37]
	s_andn2_b64 vcc, exec, s[4:5]
	s_cbranch_vccnz .LBB0_1096
	s_waitcnt vmcnt(0)
	s_waitcnt vmcnt(0) lgkmcnt(0)
	s_barrier
	s_and_saveexec_b64 s[46:47], s[82:83]
	s_cbranch_execz .LBB0_1095
	s_add_i32 s3, 0, 0x20000
	v_mov_b32_e32 v0, s3
	s_waitcnt vmcnt(0) expcnt(0) lgkmcnt(0)
	ds_read_b32 v2, v0
	s_add_i32 s3, 0, 0x20004
	v_mov_b32_e32 v0, s3
	ds_read_b32 v0, v0
	s_waitcnt lgkmcnt(1)
	v_cmp_ne_u32_e32 vcc, 0, v2
	s_cbranch_vccnz .LBB0_1066
	s_add_u32 s4, s42, 0x51fda00
	s_addc_u32 s5, s43, 0
	s_add_u32 s8, s42, 0x51fdc00
	s_addc_u32 s9, s43, 0
	s_add_u32 s10, s42, 0x51fdd00
	s_addc_u32 s11, s43, 0
	s_add_u32 s12, s42, 0x51fde00
	s_addc_u32 s13, s43, 0
	s_add_u32 s14, s42, 0x51fdf00
	s_addc_u32 s15, s43, 0
	s_add_u32 s16, s42, 0x51fe000
	s_addc_u32 s17, s43, 0
	s_add_u32 s18, s42, 0x51fe100
	s_addc_u32 s19, s43, 0
	s_add_u32 s20, s42, 0x51fe200
	s_addc_u32 s21, s43, 0
	s_add_u32 s22, s42, 0x51fe300
	s_addc_u32 s23, s43, 0
	s_add_u32 s26, s42, 0x51fe400
	s_addc_u32 s27, s43, 0
	s_add_u32 s28, s42, 0x51fe500
	s_addc_u32 s29, s43, 0
	s_add_u32 s30, s42, 0x51fe600
	s_addc_u32 s31, s43, 0
	s_add_u32 s34, s42, 0x51fe700
	s_addc_u32 s35, s43, 0
	s_add_u32 s40, s42, 0x51fe800
	s_addc_u32 s41, s43, 0
	s_load_dwordx2 s[6:7], s[80:81], 0x4
	s_add_u32 s44, s42, 0x51fe900
	s_addc_u32 s45, s43, 0
	s_add_u32 s48, s42, 0x51fea00
	s_addc_u32 s49, s43, 0
	s_add_u32 s50, s42, 0x51feb00
	s_waitcnt lgkmcnt(0)
	s_mul_i32 s3, s6, s38
	s_addc_u32 s51, s43, 0
	s_mul_i32 s3, s3, s7
	s_mov_b32 s24, 1
	s_mov_b64 s[6:7], 0
	v_mov_b64_e32 v[0:1], s[8:9]
	v_mov_b64_e32 v[2:3], s[10:11]
	v_mov_b64_e32 v[4:5], s[12:13]
	v_mov_b64_e32 v[6:7], s[14:15]
	v_mov_b64_e32 v[8:9], s[16:17]
	v_mov_b64_e32 v[10:11], s[18:19]
	v_mov_b64_e32 v[12:13], s[20:21]
	v_mov_b64_e32 v[14:15], s[22:23]
	v_mov_b64_e32 v[16:17], s[26:27]
	v_mov_b64_e32 v[18:19], s[28:29]
	v_mov_b64_e32 v[20:21], s[30:31]
	v_mov_b64_e32 v[22:23], s[34:35]
	v_mov_b64_e32 v[24:25], s[40:41]
	v_mov_b64_e32 v[26:27], s[44:45]
	v_mov_b64_e32 v[28:29], s[48:49]
	v_mov_b64_e32 v[30:31], s[50:51]
	s_branch .LBB0_1056
